# GEMM K-loops: back-edge rotation (counter/pointer SALU moved in front of the loop-back barrier; exit path has its own barrier copy)
# baseline (speedup 1.0000x reference)
.LBB0_205:
	s_add_u32 s22, s22, 0x40080
	s_addc_u32 s23, s23, 0
	v_add_u32_e32 v1, s39, v1
	v_add_u32_e32 v134, s45, v0
	s_add_u32 s15, s24, 0x100
	v_mov_b32_e32 v0, 0
	v_mov_b32_e32 v131, v173
	v_mov_b32_e32 v129, v173
	v_mov_b32_e32 v133, v173
	s_addc_u32 s17, s25, 0
	s_mov_b32 s61, -2
	v_add_u32_e32 v135, 0, v1
	v_mov_b32_e32 v1, v0
	v_mov_b32_e32 v2, v0
	v_mov_b32_e32 v3, v0
	v_mov_b32_e32 v4, v0
	v_mov_b32_e32 v5, v0
	v_mov_b32_e32 v6, v0
	v_mov_b32_e32 v7, v0
	v_mov_b32_e32 v8, v0
	v_mov_b32_e32 v9, v0
	v_mov_b32_e32 v10, v0
	v_mov_b32_e32 v11, v0
	v_mov_b32_e32 v16, v0
	v_mov_b32_e32 v17, v0
	v_mov_b32_e32 v18, v0
	v_mov_b32_e32 v19, v0
	v_mov_b32_e32 v24, v0
	v_mov_b32_e32 v25, v0
	v_mov_b32_e32 v26, v0
	v_mov_b32_e32 v27, v0
	v_mov_b32_e32 v32, v0
	v_mov_b32_e32 v33, v0
	v_mov_b32_e32 v34, v0
	v_mov_b32_e32 v35, v0
	v_mov_b32_e32 v40, v0
	v_mov_b32_e32 v41, v0
	v_mov_b32_e32 v42, v0
	v_mov_b32_e32 v43, v0
	v_mov_b32_e32 v48, v0
	v_mov_b32_e32 v49, v0
	v_mov_b32_e32 v50, v0
	v_mov_b32_e32 v51, v0
	v_mov_b32_e32 v12, v0
	v_mov_b32_e32 v13, v0
	v_mov_b32_e32 v14, v0
	v_mov_b32_e32 v15, v0
	v_mov_b32_e32 v20, v0
	v_mov_b32_e32 v21, v0
	v_mov_b32_e32 v22, v0
	v_mov_b32_e32 v23, v0
	v_mov_b32_e32 v28, v0
	v_mov_b32_e32 v29, v0
	v_mov_b32_e32 v30, v0
	v_mov_b32_e32 v31, v0
	v_mov_b32_e32 v36, v0
	v_mov_b32_e32 v37, v0
	v_mov_b32_e32 v38, v0
	v_mov_b32_e32 v39, v0
	v_mov_b32_e32 v44, v0
	v_mov_b32_e32 v45, v0
	v_mov_b32_e32 v46, v0
	v_mov_b32_e32 v47, v0
	v_mov_b32_e32 v52, v0
	v_mov_b32_e32 v53, v0
	v_mov_b32_e32 v54, v0
	v_mov_b32_e32 v55, v0
	v_mov_b32_e32 v56, v0
	v_mov_b32_e32 v57, v0
	v_mov_b32_e32 v58, v0
	v_mov_b32_e32 v59, v0
	v_mov_b32_e32 v60, v0
	v_mov_b32_e32 v61, v0
	v_mov_b32_e32 v62, v0
	v_mov_b32_e32 v63, v0
	v_mov_b32_e32 v64, v0
	v_mov_b32_e32 v65, v0
	v_mov_b32_e32 v66, v0
	v_mov_b32_e32 v67, v0
	v_mov_b32_e32 v68, v0
	v_mov_b32_e32 v69, v0
	v_mov_b32_e32 v70, v0
	v_mov_b32_e32 v71, v0
	v_mov_b32_e32 v72, v0
	v_mov_b32_e32 v73, v0
	v_mov_b32_e32 v74, v0
	v_mov_b32_e32 v75, v0
	v_mov_b32_e32 v80, v0
	v_mov_b32_e32 v81, v0
	v_mov_b32_e32 v82, v0
	v_mov_b32_e32 v83, v0
	v_mov_b32_e32 v88, v0
	v_mov_b32_e32 v89, v0
	v_mov_b32_e32 v90, v0
	v_mov_b32_e32 v91, v0
	v_mov_b32_e32 v96, v0
	v_mov_b32_e32 v97, v0
	v_mov_b32_e32 v98, v0
	v_mov_b32_e32 v99, v0
	v_mov_b32_e32 v104, v0
	v_mov_b32_e32 v105, v0
	v_mov_b32_e32 v106, v0
	v_mov_b32_e32 v107, v0
	v_mov_b32_e32 v112, v0
	v_mov_b32_e32 v113, v0
	v_mov_b32_e32 v114, v0
	v_mov_b32_e32 v115, v0
	v_mov_b32_e32 v76, v0
	v_mov_b32_e32 v77, v0
	v_mov_b32_e32 v78, v0
	v_mov_b32_e32 v79, v0
	v_mov_b32_e32 v84, v0
	v_mov_b32_e32 v85, v0
	v_mov_b32_e32 v86, v0
	v_mov_b32_e32 v87, v0
	v_mov_b32_e32 v92, v0
	v_mov_b32_e32 v93, v0
	v_mov_b32_e32 v94, v0
	v_mov_b32_e32 v95, v0
	v_mov_b32_e32 v100, v0
	v_mov_b32_e32 v101, v0
	v_mov_b32_e32 v102, v0
	v_mov_b32_e32 v103, v0
	v_mov_b32_e32 v108, v0
	v_mov_b32_e32 v109, v0
	v_mov_b32_e32 v110, v0
	v_mov_b32_e32 v111, v0
	v_mov_b32_e32 v116, v0
	v_mov_b32_e32 v117, v0
	v_mov_b32_e32 v118, v0
	v_mov_b32_e32 v119, v0
	v_mov_b32_e32 v120, v0
	v_mov_b32_e32 v121, v0
	v_mov_b32_e32 v122, v0
	v_mov_b32_e32 v123, v0
	v_mov_b32_e32 v124, v0
	v_mov_b32_e32 v125, v0
	v_mov_b32_e32 v126, v0
	v_mov_b32_e32 v127, v0
	s_add_u32 s24, s22, 0xfffc0080
	s_addc_u32 s25, s23, -1
	s_add_i32 s62, 0, 0x10000
	s_cmp_eq_u32 s61, 12
	s_cselect_b32 s27, s19, s25
	s_cselect_b32 s26, s18, s24
	s_cselect_b32 s25, s21, s17
	s_cselect_b32 s24, s20, s15
	s_add_i32 s64, 0, 0x14000
.LBB0_206:
	v_add_u32_e32 v148, s62, v134
	v_add_u32_e32 v164, s64, v134
	ds_read_b128 v[136:139], v148
	ds_read_b128 v[140:143], v148 offset:1024
	ds_read_b128 v[144:147], v148 offset:2048
	ds_read_b128 v[148:151], v148 offset:3072
	ds_read_b128 v[152:155], v164
	ds_read_b128 v[156:159], v164 offset:1024
	ds_read_b128 v[160:163], v164 offset:2048
	ds_read_b128 v[164:167], v164 offset:3072
	v_lshl_add_u64 v[174:175], s[22:23], 0, v[172:173]
	s_add_i32 m0, s34, 0xc000
	ds_read_b128 v[168:171], v135
	ds_read_b128 v[188:191], v135 offset:1024
	ds_read_b128 v[204:207], v135 offset:2048
	ds_read_b128 v[208:211], v135 offset:3072
	ds_read_b128 v[212:215], v135 offset:4096
	ds_read_b128 v[216:219], v135 offset:5120
	ds_read_b128 v[220:223], v135 offset:6144
	ds_read_b128 v[224:227], v135 offset:7168
	global_load_lds_dwordx4 v[174:175], off
	v_lshl_add_u64 v[174:175], s[22:23], 0, v[130:131]
	s_add_i32 m0, s34, 0xe000
	s_nop 0
	global_load_lds_dwordx4 v[174:175], off
	s_waitcnt vmcnt(8)
	s_waitcnt lgkmcnt(0)
	s_barrier
	s_setprio 1
	s_waitcnt lgkmcnt(0)
	v_mfma_f32_16x16x32_bf16 v[124:127], v[136:139], v[168:171], v[124:127]
	v_mfma_f32_16x16x32_bf16 v[120:123], v[144:147], v[168:171], v[120:123]
	v_mfma_f32_16x16x32_bf16 v[116:119], v[136:139], v[204:207], v[116:119]
	v_mfma_f32_16x16x32_bf16 v[108:111], v[144:147], v[204:207], v[108:111]
	v_mfma_f32_16x16x32_bf16 v[100:103], v[136:139], v[212:215], v[100:103]
	v_mfma_f32_16x16x32_bf16 v[92:95], v[144:147], v[212:215], v[92:95]
	v_mfma_f32_16x16x32_bf16 v[84:87], v[136:139], v[220:223], v[84:87]
	v_mfma_f32_16x16x32_bf16 v[76:79], v[144:147], v[220:223], v[76:79]
	v_mfma_f32_16x16x32_bf16 v[124:127], v[140:143], v[188:191], v[124:127]
	v_mfma_f32_16x16x32_bf16 v[120:123], v[148:151], v[188:191], v[120:123]
	v_mfma_f32_16x16x32_bf16 v[116:119], v[140:143], v[208:211], v[116:119]
	v_mfma_f32_16x16x32_bf16 v[108:111], v[148:151], v[208:211], v[108:111]
	v_mfma_f32_16x16x32_bf16 v[100:103], v[140:143], v[216:219], v[100:103]
	v_mfma_f32_16x16x32_bf16 v[92:95], v[148:151], v[216:219], v[92:95]
	v_mfma_f32_16x16x32_bf16 v[84:87], v[140:143], v[224:227], v[84:87]
	v_mfma_f32_16x16x32_bf16 v[76:79], v[148:151], v[224:227], v[76:79]
	s_setprio 0
	s_setprio 1
	v_mfma_f32_16x16x32_bf16 v[112:115], v[152:155], v[168:171], v[112:115]
	v_mfma_f32_16x16x32_bf16 v[104:107], v[160:163], v[168:171], v[104:107]
	v_mfma_f32_16x16x32_bf16 v[96:99], v[152:155], v[204:207], v[96:99]
	v_mfma_f32_16x16x32_bf16 v[88:91], v[160:163], v[204:207], v[88:91]
	v_mfma_f32_16x16x32_bf16 v[80:83], v[152:155], v[212:215], v[80:83]
	v_mfma_f32_16x16x32_bf16 v[72:75], v[160:163], v[212:215], v[72:75]
	v_mfma_f32_16x16x32_bf16 v[68:71], v[152:155], v[220:223], v[68:71]
	v_mfma_f32_16x16x32_bf16 v[64:67], v[160:163], v[220:223], v[64:67]
	v_mfma_f32_16x16x32_bf16 v[112:115], v[156:159], v[188:191], v[112:115]
	v_mfma_f32_16x16x32_bf16 v[104:107], v[164:167], v[188:191], v[104:107]
	v_mfma_f32_16x16x32_bf16 v[96:99], v[156:159], v[208:211], v[96:99]
	v_mfma_f32_16x16x32_bf16 v[88:91], v[164:167], v[208:211], v[88:91]
	v_mfma_f32_16x16x32_bf16 v[80:83], v[156:159], v[216:219], v[80:83]
	v_mfma_f32_16x16x32_bf16 v[72:75], v[164:167], v[216:219], v[72:75]
	v_mfma_f32_16x16x32_bf16 v[68:71], v[156:159], v[224:227], v[68:71]
	v_mfma_f32_16x16x32_bf16 v[64:67], v[164:167], v[224:227], v[64:67]
	s_setprio 0
	s_barrier
	s_add_i32 s62, s62, s31
	v_lshl_add_u64 v[174:175], s[24:25], 0, v[128:129]
	s_mov_b32 m0, s62
	ds_read_b128 v[168:171], v135 offset:16384
	ds_read_b128 v[188:191], v135 offset:17408
	ds_read_b128 v[204:207], v135 offset:18432
	ds_read_b128 v[208:211], v135 offset:19456
	ds_read_b128 v[212:215], v135 offset:20480
	ds_read_b128 v[216:219], v135 offset:21504
	ds_read_b128 v[220:223], v135 offset:22528
	ds_read_b128 v[224:227], v135 offset:23552
	global_load_lds_dwordx4 v[174:175], off
	s_add_i32 m0, s62, 0x2000
	s_add_u32 s62, s24, 0x40000
	v_lshl_add_u64 v[176:177], s[24:25], 0, v[132:133]
	s_addc_u32 s63, s25, 0
	s_add_i32 s64, s64, s31
	global_load_lds_dwordx4 v[176:177], off
	v_lshl_add_u64 v[180:181], s[62:63], 0, v[128:129]
	s_mov_b32 m0, s64
	v_lshl_add_u64 v[182:183], s[26:27], 0, v[130:131]
	global_load_lds_dwordx4 v[180:181], off
	v_lshl_add_u64 v[180:181], s[62:63], 0, v[132:133]
	s_add_i32 m0, s64, 0x2000
	s_nop 0
	global_load_lds_dwordx4 v[180:181], off
	v_lshl_add_u64 v[180:181], s[26:27], 0, v[172:173]
	s_mov_b32 m0, s34
	s_nop 0
	global_load_lds_dwordx4 v[180:181], off
	s_mov_b32 m0, s35
	s_nop 0
	global_load_lds_dwordx4 v[182:183], off
	s_waitcnt vmcnt(8)
	s_waitcnt lgkmcnt(0)
	s_barrier
	s_setprio 1
	s_waitcnt lgkmcnt(0)
	v_mfma_f32_16x16x32_bf16 v[60:63], v[136:139], v[168:171], v[60:63]
	v_mfma_f32_16x16x32_bf16 v[56:59], v[144:147], v[168:171], v[56:59]
	v_mfma_f32_16x16x32_bf16 v[52:55], v[136:139], v[204:207], v[52:55]
	v_mfma_f32_16x16x32_bf16 v[44:47], v[144:147], v[204:207], v[44:47]
	v_mfma_f32_16x16x32_bf16 v[36:39], v[136:139], v[212:215], v[36:39]
	v_mfma_f32_16x16x32_bf16 v[28:31], v[144:147], v[212:215], v[28:31]
	v_mfma_f32_16x16x32_bf16 v[20:23], v[136:139], v[220:223], v[20:23]
	v_mfma_f32_16x16x32_bf16 v[12:15], v[144:147], v[220:223], v[12:15]
	v_mfma_f32_16x16x32_bf16 v[60:63], v[140:143], v[188:191], v[60:63]
	v_mfma_f32_16x16x32_bf16 v[56:59], v[148:151], v[188:191], v[56:59]
	v_mfma_f32_16x16x32_bf16 v[52:55], v[140:143], v[208:211], v[52:55]
	v_mfma_f32_16x16x32_bf16 v[44:47], v[148:151], v[208:211], v[44:47]
	v_mfma_f32_16x16x32_bf16 v[36:39], v[140:143], v[216:219], v[36:39]
	v_mfma_f32_16x16x32_bf16 v[28:31], v[148:151], v[216:219], v[28:31]
	v_mfma_f32_16x16x32_bf16 v[20:23], v[140:143], v[224:227], v[20:23]
	v_mfma_f32_16x16x32_bf16 v[12:15], v[148:151], v[224:227], v[12:15]
	s_setprio 0
	s_setprio 1
	v_mfma_f32_16x16x32_bf16 v[48:51], v[152:155], v[168:171], v[48:51]
	v_mfma_f32_16x16x32_bf16 v[40:43], v[160:163], v[168:171], v[40:43]
	v_mfma_f32_16x16x32_bf16 v[32:35], v[152:155], v[204:207], v[32:35]
	v_mfma_f32_16x16x32_bf16 v[24:27], v[160:163], v[204:207], v[24:27]
	v_mfma_f32_16x16x32_bf16 v[16:19], v[152:155], v[212:215], v[16:19]
	v_mfma_f32_16x16x32_bf16 v[8:11], v[160:163], v[212:215], v[8:11]
	v_mfma_f32_16x16x32_bf16 v[4:7], v[152:155], v[220:223], v[4:7]
	v_mfma_f32_16x16x32_bf16 v[0:3], v[160:163], v[220:223], v[0:3]
	v_mfma_f32_16x16x32_bf16 v[48:51], v[156:159], v[188:191], v[48:51]
	v_mfma_f32_16x16x32_bf16 v[40:43], v[164:167], v[188:191], v[40:43]
	v_mfma_f32_16x16x32_bf16 v[32:35], v[156:159], v[208:211], v[32:35]
	v_mfma_f32_16x16x32_bf16 v[24:27], v[164:167], v[208:211], v[24:27]
	v_mfma_f32_16x16x32_bf16 v[16:19], v[156:159], v[216:219], v[16:19]
	v_mfma_f32_16x16x32_bf16 v[8:11], v[164:167], v[216:219], v[8:11]
	v_mfma_f32_16x16x32_bf16 v[4:7], v[156:159], v[224:227], v[4:7]
	v_mfma_f32_16x16x32_bf16 v[0:3], v[164:167], v[224:227], v[0:3]
	s_setprio 0
	s_barrier
	s_add_i32 s62, 0, 0x18000
	s_add_i32 s63, 0, 0x1c000
	v_add_u32_e32 v148, s62, v134
	v_add_u32_e32 v164, s63, v134
	ds_read_b128 v[136:139], v148
	ds_read_b128 v[140:143], v148 offset:1024
	ds_read_b128 v[144:147], v148 offset:2048
	ds_read_b128 v[148:151], v148 offset:3072
	ds_read_b128 v[152:155], v164
	ds_read_b128 v[156:159], v164 offset:1024
	ds_read_b128 v[160:163], v164 offset:2048
	ds_read_b128 v[164:167], v164 offset:3072
	s_add_u32 s26, s26, 0x40000
	s_addc_u32 s27, s27, 0
	s_mov_b32 m0, s36
	v_lshl_add_u64 v[228:229], s[26:27], 0, v[172:173]
	ds_read_b128 v[168:171], v135 offset:32768
	ds_read_b128 v[188:191], v135 offset:33792
	ds_read_b128 v[204:207], v135 offset:34816
	ds_read_b128 v[208:211], v135 offset:35840
	ds_read_b128 v[212:215], v135 offset:36864
	ds_read_b128 v[216:219], v135 offset:37888
	ds_read_b128 v[220:223], v135 offset:38912
	ds_read_b128 v[224:227], v135 offset:39936
	global_load_lds_dwordx4 v[228:229], off
	v_lshl_add_u64 v[228:229], s[26:27], 0, v[130:131]
	s_mov_b32 m0, s37
	s_nop 0
	global_load_lds_dwordx4 v[228:229], off
	s_waitcnt vmcnt(8)
	s_waitcnt lgkmcnt(0)
	s_barrier
	s_setprio 1
	s_waitcnt lgkmcnt(0)
	v_mfma_f32_16x16x32_bf16 v[124:127], v[136:139], v[168:171], v[124:127]
	v_mfma_f32_16x16x32_bf16 v[120:123], v[144:147], v[168:171], v[120:123]
	v_mfma_f32_16x16x32_bf16 v[116:119], v[136:139], v[204:207], v[116:119]
	v_mfma_f32_16x16x32_bf16 v[108:111], v[144:147], v[204:207], v[108:111]
	v_mfma_f32_16x16x32_bf16 v[100:103], v[136:139], v[212:215], v[100:103]
	v_mfma_f32_16x16x32_bf16 v[92:95], v[144:147], v[212:215], v[92:95]
	v_mfma_f32_16x16x32_bf16 v[84:87], v[136:139], v[220:223], v[84:87]
	v_mfma_f32_16x16x32_bf16 v[76:79], v[144:147], v[220:223], v[76:79]
	v_mfma_f32_16x16x32_bf16 v[124:127], v[140:143], v[188:191], v[124:127]
	v_mfma_f32_16x16x32_bf16 v[120:123], v[148:151], v[188:191], v[120:123]
	v_mfma_f32_16x16x32_bf16 v[116:119], v[140:143], v[208:211], v[116:119]
	v_mfma_f32_16x16x32_bf16 v[108:111], v[148:151], v[208:211], v[108:111]
	v_mfma_f32_16x16x32_bf16 v[100:103], v[140:143], v[216:219], v[100:103]
	v_mfma_f32_16x16x32_bf16 v[92:95], v[148:151], v[216:219], v[92:95]
	v_mfma_f32_16x16x32_bf16 v[84:87], v[140:143], v[224:227], v[84:87]
	v_mfma_f32_16x16x32_bf16 v[76:79], v[148:151], v[224:227], v[76:79]
	s_setprio 0
	s_setprio 1
	v_mfma_f32_16x16x32_bf16 v[112:115], v[152:155], v[168:171], v[112:115]
	v_mfma_f32_16x16x32_bf16 v[104:107], v[160:163], v[168:171], v[104:107]
	v_mfma_f32_16x16x32_bf16 v[96:99], v[152:155], v[204:207], v[96:99]
	v_mfma_f32_16x16x32_bf16 v[88:91], v[160:163], v[204:207], v[88:91]
	v_mfma_f32_16x16x32_bf16 v[80:83], v[152:155], v[212:215], v[80:83]
	v_mfma_f32_16x16x32_bf16 v[72:75], v[160:163], v[212:215], v[72:75]
	v_mfma_f32_16x16x32_bf16 v[68:71], v[152:155], v[220:223], v[68:71]
	v_mfma_f32_16x16x32_bf16 v[64:67], v[160:163], v[220:223], v[64:67]
	v_mfma_f32_16x16x32_bf16 v[112:115], v[156:159], v[188:191], v[112:115]
	v_mfma_f32_16x16x32_bf16 v[104:107], v[164:167], v[188:191], v[104:107]
	v_mfma_f32_16x16x32_bf16 v[96:99], v[156:159], v[208:211], v[96:99]
	v_mfma_f32_16x16x32_bf16 v[88:91], v[164:167], v[208:211], v[88:91]
	v_mfma_f32_16x16x32_bf16 v[80:83], v[156:159], v[216:219], v[80:83]
	v_mfma_f32_16x16x32_bf16 v[72:75], v[164:167], v[216:219], v[72:75]
	v_mfma_f32_16x16x32_bf16 v[68:71], v[156:159], v[224:227], v[68:71]
	v_mfma_f32_16x16x32_bf16 v[64:67], v[164:167], v[224:227], v[64:67]
	s_setprio 0
	s_barrier
	s_add_i32 s26, s62, s31
	v_lshl_add_u64 v[174:175], v[174:175], 0, s[94:95]
	s_mov_b32 m0, s26
	ds_read_b128 v[168:171], v135 offset:49152
	ds_read_b128 v[188:191], v135 offset:50176
	ds_read_b128 v[204:207], v135 offset:51200
	ds_read_b128 v[208:211], v135 offset:52224
	ds_read_b128 v[212:215], v135 offset:53248
	ds_read_b128 v[216:219], v135 offset:54272
	ds_read_b128 v[220:223], v135 offset:55296
	ds_read_b128 v[224:227], v135 offset:56320
	global_load_lds_dwordx4 v[174:175], off
	s_add_i32 m0, s26, 0x2000
	s_add_u32 s24, s24, 0x40080
	v_lshl_add_u64 v[174:175], v[176:177], 0, s[94:95]
	s_addc_u32 s25, s25, 0
	s_add_i32 s26, s63, s31
	global_load_lds_dwordx4 v[174:175], off
	v_lshl_add_u64 v[174:175], s[24:25], 0, v[128:129]
	s_mov_b32 m0, s26
	s_nop 0
	global_load_lds_dwordx4 v[174:175], off
	v_lshl_add_u64 v[174:175], s[24:25], 0, v[132:133]
	s_add_i32 m0, s26, 0x2000
	s_nop 0
	global_load_lds_dwordx4 v[174:175], off
	v_lshl_add_u64 v[174:175], v[180:181], 0, s[94:95]
	s_mov_b32 m0, s54
	s_nop 0
	global_load_lds_dwordx4 v[174:175], off
	v_lshl_add_u64 v[174:175], v[182:183], 0, s[94:95]
	s_mov_b32 m0, s55
	s_nop 0
	global_load_lds_dwordx4 v[174:175], off
	s_waitcnt vmcnt(8)
	s_waitcnt lgkmcnt(0)
	s_barrier
	s_setprio 1
	s_waitcnt lgkmcnt(0)
	v_mfma_f32_16x16x32_bf16 v[60:63], v[136:139], v[168:171], v[60:63]
	v_mfma_f32_16x16x32_bf16 v[56:59], v[144:147], v[168:171], v[56:59]
	v_mfma_f32_16x16x32_bf16 v[52:55], v[136:139], v[204:207], v[52:55]
	v_mfma_f32_16x16x32_bf16 v[44:47], v[144:147], v[204:207], v[44:47]
	v_mfma_f32_16x16x32_bf16 v[36:39], v[136:139], v[212:215], v[36:39]
	v_mfma_f32_16x16x32_bf16 v[28:31], v[144:147], v[212:215], v[28:31]
	v_mfma_f32_16x16x32_bf16 v[20:23], v[136:139], v[220:223], v[20:23]
	v_mfma_f32_16x16x32_bf16 v[12:15], v[144:147], v[220:223], v[12:15]
	v_mfma_f32_16x16x32_bf16 v[60:63], v[140:143], v[188:191], v[60:63]
	v_mfma_f32_16x16x32_bf16 v[56:59], v[148:151], v[188:191], v[56:59]
	v_mfma_f32_16x16x32_bf16 v[52:55], v[140:143], v[208:211], v[52:55]
	v_mfma_f32_16x16x32_bf16 v[44:47], v[148:151], v[208:211], v[44:47]
	v_mfma_f32_16x16x32_bf16 v[36:39], v[140:143], v[216:219], v[36:39]
	v_mfma_f32_16x16x32_bf16 v[28:31], v[148:151], v[216:219], v[28:31]
	v_mfma_f32_16x16x32_bf16 v[20:23], v[140:143], v[224:227], v[20:23]
	v_mfma_f32_16x16x32_bf16 v[12:15], v[148:151], v[224:227], v[12:15]
	s_setprio 0
	s_setprio 1
	v_mfma_f32_16x16x32_bf16 v[48:51], v[152:155], v[168:171], v[48:51]
	v_mfma_f32_16x16x32_bf16 v[40:43], v[160:163], v[168:171], v[40:43]
	v_mfma_f32_16x16x32_bf16 v[32:35], v[152:155], v[204:207], v[32:35]
	v_mfma_f32_16x16x32_bf16 v[24:27], v[160:163], v[204:207], v[24:27]
	v_mfma_f32_16x16x32_bf16 v[16:19], v[152:155], v[212:215], v[16:19]
	v_mfma_f32_16x16x32_bf16 v[8:11], v[160:163], v[212:215], v[8:11]
	v_mfma_f32_16x16x32_bf16 v[4:7], v[152:155], v[220:223], v[4:7]
	v_mfma_f32_16x16x32_bf16 v[0:3], v[160:163], v[220:223], v[0:3]
	v_mfma_f32_16x16x32_bf16 v[48:51], v[156:159], v[188:191], v[48:51]
	v_mfma_f32_16x16x32_bf16 v[40:43], v[164:167], v[188:191], v[40:43]
	v_mfma_f32_16x16x32_bf16 v[32:35], v[156:159], v[208:211], v[32:35]
	v_mfma_f32_16x16x32_bf16 v[24:27], v[164:167], v[208:211], v[24:27]
	v_mfma_f32_16x16x32_bf16 v[16:19], v[156:159], v[216:219], v[16:19]
	v_mfma_f32_16x16x32_bf16 v[8:11], v[164:167], v[216:219], v[8:11]
	v_mfma_f32_16x16x32_bf16 v[4:7], v[156:159], v[224:227], v[4:7]
	v_mfma_f32_16x16x32_bf16 v[0:3], v[164:167], v[224:227], v[0:3]
	s_setprio 0
	s_add_i32 s61, s61, 2
	s_add_u32 s22, s22, 0x100
	s_addc_u32 s23, s23, 0
	s_add_u32 s15, s15, 0x100
	s_addc_u32 s17, s17, 0
	s_cmp_gt_u32 s61, 13
	s_cbranch_scc1 .Lkrot0_exit
	s_add_u32 s24, s22, 0xfffc0080
	s_addc_u32 s25, s23, -1
	s_add_i32 s62, 0, 0x10000
	s_cmp_eq_u32 s61, 12
	s_cselect_b32 s27, s19, s25
	s_cselect_b32 s26, s18, s24
	s_cselect_b32 s25, s21, s17
	s_cselect_b32 s24, s20, s15
	s_add_i32 s64, 0, 0x14000
	s_barrier
	s_branch .LBB0_206
.Lkrot0_exit:
	s_barrier
	s_and_b64 vcc, exec, s[12:13]
	s_cbranch_vccz .LBB0_209
	s_barrier

.LBB0_588:
	s_add_i32 s65, s62, -2
	s_add_u32 s18, s18, 0x60080
	s_addc_u32 s19, s19, 0
	v_add_u32_e32 v1, s38, v1
	v_add_u32_e32 v134, s44, v0
	s_add_u32 s66, s20, 0x100
	v_mov_b32_e32 v0, 0
	v_mov_b32_e32 v131, v173
	v_mov_b32_e32 v129, v173
	v_mov_b32_e32 v133, v173
	s_addc_u32 s67, s21, 0
	s_mov_b32 s20, 0
	v_add_u32_e32 v135, 0, v1
	v_mov_b32_e32 v1, v0
	v_mov_b32_e32 v2, v0
	v_mov_b32_e32 v3, v0
	v_mov_b32_e32 v4, v0
	v_mov_b32_e32 v5, v0
	v_mov_b32_e32 v6, v0
	v_mov_b32_e32 v7, v0
	v_mov_b32_e32 v8, v0
	v_mov_b32_e32 v9, v0
	v_mov_b32_e32 v10, v0
	v_mov_b32_e32 v11, v0
	v_mov_b32_e32 v16, v0
	v_mov_b32_e32 v17, v0
	v_mov_b32_e32 v18, v0
	v_mov_b32_e32 v19, v0
	v_mov_b32_e32 v24, v0
	v_mov_b32_e32 v25, v0
	v_mov_b32_e32 v26, v0
	v_mov_b32_e32 v27, v0
	v_mov_b32_e32 v32, v0
	v_mov_b32_e32 v33, v0
	v_mov_b32_e32 v34, v0
	v_mov_b32_e32 v35, v0
	v_mov_b32_e32 v40, v0
	v_mov_b32_e32 v41, v0
	v_mov_b32_e32 v42, v0
	v_mov_b32_e32 v43, v0
	v_mov_b32_e32 v48, v0
	v_mov_b32_e32 v49, v0
	v_mov_b32_e32 v50, v0
	v_mov_b32_e32 v51, v0
	v_mov_b32_e32 v12, v0
	v_mov_b32_e32 v13, v0
	v_mov_b32_e32 v14, v0
	v_mov_b32_e32 v15, v0
	v_mov_b32_e32 v20, v0
	v_mov_b32_e32 v21, v0
	v_mov_b32_e32 v22, v0
	v_mov_b32_e32 v23, v0
	v_mov_b32_e32 v28, v0
	v_mov_b32_e32 v29, v0
	v_mov_b32_e32 v30, v0
	v_mov_b32_e32 v31, v0
	v_mov_b32_e32 v36, v0
	v_mov_b32_e32 v37, v0
	v_mov_b32_e32 v38, v0
	v_mov_b32_e32 v39, v0
	v_mov_b32_e32 v44, v0
	v_mov_b32_e32 v45, v0
	v_mov_b32_e32 v46, v0
	v_mov_b32_e32 v47, v0
	v_mov_b32_e32 v52, v0
	v_mov_b32_e32 v53, v0
	v_mov_b32_e32 v54, v0
	v_mov_b32_e32 v55, v0
	v_mov_b32_e32 v56, v0
	v_mov_b32_e32 v57, v0
	v_mov_b32_e32 v58, v0
	v_mov_b32_e32 v59, v0
	v_mov_b32_e32 v60, v0
	v_mov_b32_e32 v61, v0
	v_mov_b32_e32 v62, v0
	v_mov_b32_e32 v63, v0
	v_mov_b32_e32 v64, v0
	v_mov_b32_e32 v65, v0
	v_mov_b32_e32 v66, v0
	v_mov_b32_e32 v67, v0
	v_mov_b32_e32 v68, v0
	v_mov_b32_e32 v69, v0
	v_mov_b32_e32 v70, v0
	v_mov_b32_e32 v71, v0
	v_mov_b32_e32 v72, v0
	v_mov_b32_e32 v73, v0
	v_mov_b32_e32 v74, v0
	v_mov_b32_e32 v75, v0
	v_mov_b32_e32 v80, v0
	v_mov_b32_e32 v81, v0
	v_mov_b32_e32 v82, v0
	v_mov_b32_e32 v83, v0
	v_mov_b32_e32 v88, v0
	v_mov_b32_e32 v89, v0
	v_mov_b32_e32 v90, v0
	v_mov_b32_e32 v91, v0
	v_mov_b32_e32 v96, v0
	v_mov_b32_e32 v97, v0
	v_mov_b32_e32 v98, v0
	v_mov_b32_e32 v99, v0
	v_mov_b32_e32 v104, v0
	v_mov_b32_e32 v105, v0
	v_mov_b32_e32 v106, v0
	v_mov_b32_e32 v107, v0
	v_mov_b32_e32 v112, v0
	v_mov_b32_e32 v113, v0
	v_mov_b32_e32 v114, v0
	v_mov_b32_e32 v115, v0
	v_mov_b32_e32 v76, v0
	v_mov_b32_e32 v77, v0
	v_mov_b32_e32 v78, v0
	v_mov_b32_e32 v79, v0
	v_mov_b32_e32 v84, v0
	v_mov_b32_e32 v85, v0
	v_mov_b32_e32 v86, v0
	v_mov_b32_e32 v87, v0
	v_mov_b32_e32 v92, v0
	v_mov_b32_e32 v93, v0
	v_mov_b32_e32 v94, v0
	v_mov_b32_e32 v95, v0
	v_mov_b32_e32 v100, v0
	v_mov_b32_e32 v101, v0
	v_mov_b32_e32 v102, v0
	v_mov_b32_e32 v103, v0
	v_mov_b32_e32 v108, v0
	v_mov_b32_e32 v109, v0
	v_mov_b32_e32 v110, v0
	v_mov_b32_e32 v111, v0
	v_mov_b32_e32 v116, v0
	v_mov_b32_e32 v117, v0
	v_mov_b32_e32 v118, v0
	v_mov_b32_e32 v119, v0
	v_mov_b32_e32 v120, v0
	v_mov_b32_e32 v121, v0
	v_mov_b32_e32 v122, v0
	v_mov_b32_e32 v123, v0
	v_mov_b32_e32 v124, v0
	v_mov_b32_e32 v125, v0
	v_mov_b32_e32 v126, v0
	v_mov_b32_e32 v127, v0
	s_add_i32 s68, s20, 2
	s_add_u32 s21, s18, 0xfffa0080
	s_addc_u32 s22, s19, -1
	s_add_i32 s69, 0, 0x10000
	s_cmp_eq_u32 s65, s20
	s_cselect_b32 s23, s15, s22
	s_cselect_b32 s22, s14, s21
	s_cselect_b32 s21, s17, s67
	s_cselect_b32 s20, s16, s66
	s_add_i32 s72, 0, 0x14000
.LBB0_589:
	v_add_u32_e32 v148, s69, v134
	v_add_u32_e32 v164, s72, v134
	ds_read_b128 v[136:139], v148
	ds_read_b128 v[140:143], v148 offset:1024
	ds_read_b128 v[144:147], v148 offset:2048
	ds_read_b128 v[148:151], v148 offset:3072
	ds_read_b128 v[152:155], v164
	ds_read_b128 v[156:159], v164 offset:1024
	ds_read_b128 v[160:163], v164 offset:2048
	ds_read_b128 v[164:167], v164 offset:3072
	v_lshl_add_u64 v[174:175], s[18:19], 0, v[172:173]
	s_add_i32 m0, s31, 0xc000
	ds_read_b128 v[168:171], v135
	ds_read_b128 v[188:191], v135 offset:1024
	ds_read_b128 v[204:207], v135 offset:2048
	ds_read_b128 v[208:211], v135 offset:3072
	ds_read_b128 v[212:215], v135 offset:4096
	ds_read_b128 v[216:219], v135 offset:5120
	ds_read_b128 v[220:223], v135 offset:6144
	ds_read_b128 v[224:227], v135 offset:7168
	global_load_lds_dwordx4 v[174:175], off
	v_lshl_add_u64 v[174:175], s[18:19], 0, v[130:131]
	s_add_i32 m0, s31, 0xe000
	s_nop 0
	global_load_lds_dwordx4 v[174:175], off
	s_waitcnt vmcnt(8)
	s_waitcnt lgkmcnt(0)
	s_barrier
	s_setprio 1
	s_waitcnt lgkmcnt(0)
	v_mfma_f32_16x16x32_bf16 v[124:127], v[136:139], v[168:171], v[124:127]
	v_mfma_f32_16x16x32_bf16 v[120:123], v[144:147], v[168:171], v[120:123]
	v_mfma_f32_16x16x32_bf16 v[116:119], v[136:139], v[204:207], v[116:119]
	v_mfma_f32_16x16x32_bf16 v[108:111], v[144:147], v[204:207], v[108:111]
	v_mfma_f32_16x16x32_bf16 v[100:103], v[136:139], v[212:215], v[100:103]
	v_mfma_f32_16x16x32_bf16 v[92:95], v[144:147], v[212:215], v[92:95]
	v_mfma_f32_16x16x32_bf16 v[84:87], v[136:139], v[220:223], v[84:87]
	v_mfma_f32_16x16x32_bf16 v[76:79], v[144:147], v[220:223], v[76:79]
	v_mfma_f32_16x16x32_bf16 v[124:127], v[140:143], v[188:191], v[124:127]
	v_mfma_f32_16x16x32_bf16 v[120:123], v[148:151], v[188:191], v[120:123]
	v_mfma_f32_16x16x32_bf16 v[116:119], v[140:143], v[208:211], v[116:119]
	v_mfma_f32_16x16x32_bf16 v[108:111], v[148:151], v[208:211], v[108:111]
	v_mfma_f32_16x16x32_bf16 v[100:103], v[140:143], v[216:219], v[100:103]
	v_mfma_f32_16x16x32_bf16 v[92:95], v[148:151], v[216:219], v[92:95]
	v_mfma_f32_16x16x32_bf16 v[84:87], v[140:143], v[224:227], v[84:87]
	v_mfma_f32_16x16x32_bf16 v[76:79], v[148:151], v[224:227], v[76:79]
	s_setprio 0
	s_setprio 1
	v_mfma_f32_16x16x32_bf16 v[112:115], v[152:155], v[168:171], v[112:115]
	v_mfma_f32_16x16x32_bf16 v[104:107], v[160:163], v[168:171], v[104:107]
	v_mfma_f32_16x16x32_bf16 v[96:99], v[152:155], v[204:207], v[96:99]
	v_mfma_f32_16x16x32_bf16 v[88:91], v[160:163], v[204:207], v[88:91]
	v_mfma_f32_16x16x32_bf16 v[80:83], v[152:155], v[212:215], v[80:83]
	v_mfma_f32_16x16x32_bf16 v[72:75], v[160:163], v[212:215], v[72:75]
	v_mfma_f32_16x16x32_bf16 v[68:71], v[152:155], v[220:223], v[68:71]
	v_mfma_f32_16x16x32_bf16 v[64:67], v[160:163], v[220:223], v[64:67]
	v_mfma_f32_16x16x32_bf16 v[112:115], v[156:159], v[188:191], v[112:115]
	v_mfma_f32_16x16x32_bf16 v[104:107], v[164:167], v[188:191], v[104:107]
	v_mfma_f32_16x16x32_bf16 v[96:99], v[156:159], v[208:211], v[96:99]
	v_mfma_f32_16x16x32_bf16 v[88:91], v[164:167], v[208:211], v[88:91]
	v_mfma_f32_16x16x32_bf16 v[80:83], v[156:159], v[216:219], v[80:83]
	v_mfma_f32_16x16x32_bf16 v[72:75], v[164:167], v[216:219], v[72:75]
	v_mfma_f32_16x16x32_bf16 v[68:71], v[156:159], v[224:227], v[68:71]
	v_mfma_f32_16x16x32_bf16 v[64:67], v[164:167], v[224:227], v[64:67]
	s_setprio 0
	s_barrier
	s_add_i32 s69, s69, s30
	v_lshl_add_u64 v[174:175], s[20:21], 0, v[128:129]
	s_mov_b32 m0, s69
	ds_read_b128 v[168:171], v135 offset:16384
	ds_read_b128 v[188:191], v135 offset:17408
	ds_read_b128 v[204:207], v135 offset:18432
	ds_read_b128 v[208:211], v135 offset:19456
	ds_read_b128 v[212:215], v135 offset:20480
	ds_read_b128 v[216:219], v135 offset:21504
	ds_read_b128 v[220:223], v135 offset:22528
	ds_read_b128 v[224:227], v135 offset:23552
	global_load_lds_dwordx4 v[174:175], off
	s_add_i32 m0, s69, 0x2000
	s_add_u32 s70, s20, 0x60000
	v_lshl_add_u64 v[176:177], s[20:21], 0, v[132:133]
	s_addc_u32 s71, s21, 0
	s_add_i32 s69, s72, s30
	global_load_lds_dwordx4 v[176:177], off
	v_lshl_add_u64 v[180:181], s[70:71], 0, v[128:129]
	s_mov_b32 m0, s69
	v_lshl_add_u64 v[182:183], s[22:23], 0, v[130:131]
	global_load_lds_dwordx4 v[180:181], off
	v_lshl_add_u64 v[180:181], s[70:71], 0, v[132:133]
	s_add_i32 m0, s69, 0x2000
	s_nop 0
	global_load_lds_dwordx4 v[180:181], off
	v_lshl_add_u64 v[180:181], s[22:23], 0, v[172:173]
	s_mov_b32 m0, s31
	s_nop 0
	global_load_lds_dwordx4 v[180:181], off
	s_mov_b32 m0, s34
	s_nop 0
	global_load_lds_dwordx4 v[182:183], off
	s_waitcnt vmcnt(8)
	s_waitcnt lgkmcnt(0)
	s_barrier
	s_setprio 1
	s_waitcnt lgkmcnt(0)
	v_mfma_f32_16x16x32_bf16 v[60:63], v[136:139], v[168:171], v[60:63]
	v_mfma_f32_16x16x32_bf16 v[56:59], v[144:147], v[168:171], v[56:59]
	v_mfma_f32_16x16x32_bf16 v[52:55], v[136:139], v[204:207], v[52:55]
	v_mfma_f32_16x16x32_bf16 v[44:47], v[144:147], v[204:207], v[44:47]
	v_mfma_f32_16x16x32_bf16 v[36:39], v[136:139], v[212:215], v[36:39]
	v_mfma_f32_16x16x32_bf16 v[28:31], v[144:147], v[212:215], v[28:31]
	v_mfma_f32_16x16x32_bf16 v[20:23], v[136:139], v[220:223], v[20:23]
	v_mfma_f32_16x16x32_bf16 v[12:15], v[144:147], v[220:223], v[12:15]
	v_mfma_f32_16x16x32_bf16 v[60:63], v[140:143], v[188:191], v[60:63]
	v_mfma_f32_16x16x32_bf16 v[56:59], v[148:151], v[188:191], v[56:59]
	v_mfma_f32_16x16x32_bf16 v[52:55], v[140:143], v[208:211], v[52:55]
	v_mfma_f32_16x16x32_bf16 v[44:47], v[148:151], v[208:211], v[44:47]
	v_mfma_f32_16x16x32_bf16 v[36:39], v[140:143], v[216:219], v[36:39]
	v_mfma_f32_16x16x32_bf16 v[28:31], v[148:151], v[216:219], v[28:31]
	v_mfma_f32_16x16x32_bf16 v[20:23], v[140:143], v[224:227], v[20:23]
	v_mfma_f32_16x16x32_bf16 v[12:15], v[148:151], v[224:227], v[12:15]
	s_setprio 0
	s_setprio 1
	v_mfma_f32_16x16x32_bf16 v[48:51], v[152:155], v[168:171], v[48:51]
	v_mfma_f32_16x16x32_bf16 v[40:43], v[160:163], v[168:171], v[40:43]
	v_mfma_f32_16x16x32_bf16 v[32:35], v[152:155], v[204:207], v[32:35]
	v_mfma_f32_16x16x32_bf16 v[24:27], v[160:163], v[204:207], v[24:27]
	v_mfma_f32_16x16x32_bf16 v[16:19], v[152:155], v[212:215], v[16:19]
	v_mfma_f32_16x16x32_bf16 v[8:11], v[160:163], v[212:215], v[8:11]
	v_mfma_f32_16x16x32_bf16 v[4:7], v[152:155], v[220:223], v[4:7]
	v_mfma_f32_16x16x32_bf16 v[0:3], v[160:163], v[220:223], v[0:3]
	v_mfma_f32_16x16x32_bf16 v[48:51], v[156:159], v[188:191], v[48:51]
	v_mfma_f32_16x16x32_bf16 v[40:43], v[164:167], v[188:191], v[40:43]
	v_mfma_f32_16x16x32_bf16 v[32:35], v[156:159], v[208:211], v[32:35]
	v_mfma_f32_16x16x32_bf16 v[24:27], v[164:167], v[208:211], v[24:27]
	v_mfma_f32_16x16x32_bf16 v[16:19], v[156:159], v[216:219], v[16:19]
	v_mfma_f32_16x16x32_bf16 v[8:11], v[164:167], v[216:219], v[8:11]
	v_mfma_f32_16x16x32_bf16 v[4:7], v[156:159], v[224:227], v[4:7]
	v_mfma_f32_16x16x32_bf16 v[0:3], v[164:167], v[224:227], v[0:3]
	s_setprio 0
	s_barrier
	s_add_i32 s69, 0, 0x18000
	s_add_i32 s70, 0, 0x1c000
	v_add_u32_e32 v148, s69, v134
	v_add_u32_e32 v164, s70, v134
	ds_read_b128 v[136:139], v148
	ds_read_b128 v[140:143], v148 offset:1024
	ds_read_b128 v[144:147], v148 offset:2048
	ds_read_b128 v[148:151], v148 offset:3072
	ds_read_b128 v[152:155], v164
	ds_read_b128 v[156:159], v164 offset:1024
	ds_read_b128 v[160:163], v164 offset:2048
	ds_read_b128 v[164:167], v164 offset:3072
	s_add_u32 s22, s22, 0x60000
	s_addc_u32 s23, s23, 0
	s_mov_b32 m0, s35
	v_lshl_add_u64 v[228:229], s[22:23], 0, v[172:173]
	ds_read_b128 v[168:171], v135 offset:32768
	ds_read_b128 v[188:191], v135 offset:33792
	ds_read_b128 v[204:207], v135 offset:34816
	ds_read_b128 v[208:211], v135 offset:35840
	ds_read_b128 v[212:215], v135 offset:36864
	ds_read_b128 v[216:219], v135 offset:37888
	ds_read_b128 v[220:223], v135 offset:38912
	ds_read_b128 v[224:227], v135 offset:39936
	global_load_lds_dwordx4 v[228:229], off
	v_lshl_add_u64 v[228:229], s[22:23], 0, v[130:131]
	s_mov_b32 m0, s36
	s_nop 0
	global_load_lds_dwordx4 v[228:229], off
	s_waitcnt vmcnt(8)
	s_waitcnt lgkmcnt(0)
	s_barrier
	s_setprio 1
	s_waitcnt lgkmcnt(0)
	v_mfma_f32_16x16x32_bf16 v[124:127], v[136:139], v[168:171], v[124:127]
	v_mfma_f32_16x16x32_bf16 v[120:123], v[144:147], v[168:171], v[120:123]
	v_mfma_f32_16x16x32_bf16 v[116:119], v[136:139], v[204:207], v[116:119]
	v_mfma_f32_16x16x32_bf16 v[108:111], v[144:147], v[204:207], v[108:111]
	v_mfma_f32_16x16x32_bf16 v[100:103], v[136:139], v[212:215], v[100:103]
	v_mfma_f32_16x16x32_bf16 v[92:95], v[144:147], v[212:215], v[92:95]
	v_mfma_f32_16x16x32_bf16 v[84:87], v[136:139], v[220:223], v[84:87]
	v_mfma_f32_16x16x32_bf16 v[76:79], v[144:147], v[220:223], v[76:79]
	v_mfma_f32_16x16x32_bf16 v[124:127], v[140:143], v[188:191], v[124:127]
	v_mfma_f32_16x16x32_bf16 v[120:123], v[148:151], v[188:191], v[120:123]
	v_mfma_f32_16x16x32_bf16 v[116:119], v[140:143], v[208:211], v[116:119]
	v_mfma_f32_16x16x32_bf16 v[108:111], v[148:151], v[208:211], v[108:111]
	v_mfma_f32_16x16x32_bf16 v[100:103], v[140:143], v[216:219], v[100:103]
	v_mfma_f32_16x16x32_bf16 v[92:95], v[148:151], v[216:219], v[92:95]
	v_mfma_f32_16x16x32_bf16 v[84:87], v[140:143], v[224:227], v[84:87]
	v_mfma_f32_16x16x32_bf16 v[76:79], v[148:151], v[224:227], v[76:79]
	s_setprio 0
	s_setprio 1
	v_mfma_f32_16x16x32_bf16 v[112:115], v[152:155], v[168:171], v[112:115]
	v_mfma_f32_16x16x32_bf16 v[104:107], v[160:163], v[168:171], v[104:107]
	v_mfma_f32_16x16x32_bf16 v[96:99], v[152:155], v[204:207], v[96:99]
	v_mfma_f32_16x16x32_bf16 v[88:91], v[160:163], v[204:207], v[88:91]
	v_mfma_f32_16x16x32_bf16 v[80:83], v[152:155], v[212:215], v[80:83]
	v_mfma_f32_16x16x32_bf16 v[72:75], v[160:163], v[212:215], v[72:75]
	v_mfma_f32_16x16x32_bf16 v[68:71], v[152:155], v[220:223], v[68:71]
	v_mfma_f32_16x16x32_bf16 v[64:67], v[160:163], v[220:223], v[64:67]
	v_mfma_f32_16x16x32_bf16 v[112:115], v[156:159], v[188:191], v[112:115]
	v_mfma_f32_16x16x32_bf16 v[104:107], v[164:167], v[188:191], v[104:107]
	v_mfma_f32_16x16x32_bf16 v[96:99], v[156:159], v[208:211], v[96:99]
	v_mfma_f32_16x16x32_bf16 v[88:91], v[164:167], v[208:211], v[88:91]
	v_mfma_f32_16x16x32_bf16 v[80:83], v[156:159], v[216:219], v[80:83]
	v_mfma_f32_16x16x32_bf16 v[72:75], v[164:167], v[216:219], v[72:75]
	v_mfma_f32_16x16x32_bf16 v[68:71], v[156:159], v[224:227], v[68:71]
	v_mfma_f32_16x16x32_bf16 v[64:67], v[164:167], v[224:227], v[64:67]
	s_setprio 0
	s_barrier
	s_add_i32 s22, s69, s30
	v_lshl_add_u64 v[174:175], v[174:175], 0, s[94:95]
	s_mov_b32 m0, s22
	ds_read_b128 v[168:171], v135 offset:49152
	ds_read_b128 v[188:191], v135 offset:50176
	ds_read_b128 v[204:207], v135 offset:51200
	ds_read_b128 v[208:211], v135 offset:52224
	ds_read_b128 v[212:215], v135 offset:53248
	ds_read_b128 v[216:219], v135 offset:54272
	ds_read_b128 v[220:223], v135 offset:55296
	ds_read_b128 v[224:227], v135 offset:56320
	global_load_lds_dwordx4 v[174:175], off
	s_add_i32 m0, s22, 0x2000
	s_add_u32 s20, s20, 0x60080
	v_lshl_add_u64 v[174:175], v[176:177], 0, s[94:95]
	s_addc_u32 s21, s21, 0
	s_add_i32 s22, s70, s30
	global_load_lds_dwordx4 v[174:175], off
	v_lshl_add_u64 v[174:175], s[20:21], 0, v[128:129]
	s_mov_b32 m0, s22
	s_nop 0
	global_load_lds_dwordx4 v[174:175], off
	v_lshl_add_u64 v[174:175], s[20:21], 0, v[132:133]
	s_add_i32 m0, s22, 0x2000
	s_nop 0
	global_load_lds_dwordx4 v[174:175], off
	v_lshl_add_u64 v[174:175], v[180:181], 0, s[94:95]
	s_mov_b32 m0, s45
	s_nop 0
	global_load_lds_dwordx4 v[174:175], off
	v_lshl_add_u64 v[174:175], v[182:183], 0, s[94:95]
	s_mov_b32 m0, s54
	s_nop 0
	global_load_lds_dwordx4 v[174:175], off
	s_waitcnt vmcnt(8)
	s_waitcnt lgkmcnt(0)
	s_barrier
	s_setprio 1
	s_waitcnt lgkmcnt(0)
	v_mfma_f32_16x16x32_bf16 v[60:63], v[136:139], v[168:171], v[60:63]
	v_mfma_f32_16x16x32_bf16 v[56:59], v[144:147], v[168:171], v[56:59]
	v_mfma_f32_16x16x32_bf16 v[52:55], v[136:139], v[204:207], v[52:55]
	v_mfma_f32_16x16x32_bf16 v[44:47], v[144:147], v[204:207], v[44:47]
	v_mfma_f32_16x16x32_bf16 v[36:39], v[136:139], v[212:215], v[36:39]
	v_mfma_f32_16x16x32_bf16 v[28:31], v[144:147], v[212:215], v[28:31]
	v_mfma_f32_16x16x32_bf16 v[20:23], v[136:139], v[220:223], v[20:23]
	v_mfma_f32_16x16x32_bf16 v[12:15], v[144:147], v[220:223], v[12:15]
	v_mfma_f32_16x16x32_bf16 v[60:63], v[140:143], v[188:191], v[60:63]
	v_mfma_f32_16x16x32_bf16 v[56:59], v[148:151], v[188:191], v[56:59]
	v_mfma_f32_16x16x32_bf16 v[52:55], v[140:143], v[208:211], v[52:55]
	v_mfma_f32_16x16x32_bf16 v[44:47], v[148:151], v[208:211], v[44:47]
	v_mfma_f32_16x16x32_bf16 v[36:39], v[140:143], v[216:219], v[36:39]
	v_mfma_f32_16x16x32_bf16 v[28:31], v[148:151], v[216:219], v[28:31]
	v_mfma_f32_16x16x32_bf16 v[20:23], v[140:143], v[224:227], v[20:23]
	v_mfma_f32_16x16x32_bf16 v[12:15], v[148:151], v[224:227], v[12:15]
	s_setprio 0
	s_setprio 1
	v_mfma_f32_16x16x32_bf16 v[48:51], v[152:155], v[168:171], v[48:51]
	v_mfma_f32_16x16x32_bf16 v[40:43], v[160:163], v[168:171], v[40:43]
	v_mfma_f32_16x16x32_bf16 v[32:35], v[152:155], v[204:207], v[32:35]
	v_mfma_f32_16x16x32_bf16 v[24:27], v[160:163], v[204:207], v[24:27]
	v_mfma_f32_16x16x32_bf16 v[16:19], v[152:155], v[212:215], v[16:19]
	v_mfma_f32_16x16x32_bf16 v[8:11], v[160:163], v[212:215], v[8:11]
	v_mfma_f32_16x16x32_bf16 v[4:7], v[152:155], v[220:223], v[4:7]
	v_mfma_f32_16x16x32_bf16 v[0:3], v[160:163], v[220:223], v[0:3]
	v_mfma_f32_16x16x32_bf16 v[48:51], v[156:159], v[188:191], v[48:51]
	v_mfma_f32_16x16x32_bf16 v[40:43], v[164:167], v[188:191], v[40:43]
	v_mfma_f32_16x16x32_bf16 v[32:35], v[156:159], v[208:211], v[32:35]
	v_mfma_f32_16x16x32_bf16 v[24:27], v[164:167], v[208:211], v[24:27]
	v_mfma_f32_16x16x32_bf16 v[16:19], v[156:159], v[216:219], v[16:19]
	v_mfma_f32_16x16x32_bf16 v[8:11], v[164:167], v[216:219], v[8:11]
	v_mfma_f32_16x16x32_bf16 v[4:7], v[156:159], v[224:227], v[4:7]
	v_mfma_f32_16x16x32_bf16 v[0:3], v[164:167], v[224:227], v[0:3]
	s_setprio 0
	s_add_u32 s18, s18, 0x100
	s_addc_u32 s19, s19, 0
	s_add_u32 s66, s66, 0x100
	s_addc_u32 s67, s67, 0
	s_cmp_ge_i32 s68, s62
	s_mov_b32 s20, s68
	s_cbranch_scc1 .Lkrot1_exit
	s_add_i32 s68, s20, 2
	s_add_u32 s21, s18, 0xfffa0080
	s_addc_u32 s22, s19, -1
	s_add_i32 s69, 0, 0x10000
	s_cmp_eq_u32 s65, s20
	s_cselect_b32 s23, s15, s22
	s_cselect_b32 s22, s14, s21
	s_cselect_b32 s21, s17, s67
	s_cselect_b32 s20, s16, s66
	s_add_i32 s72, 0, 0x14000
	s_barrier
	s_branch .LBB0_589
.Lkrot1_exit:
	s_barrier
	s_and_b64 vcc, exec, s[10:11]
	s_cbranch_vccz .LBB0_592
	s_barrier

.LBB0_670:
	s_add_u32 s34, s34, 0x40080
	s_addc_u32 s35, s35, 0
	v_add_u32_e32 v1, s67, v1
	v_add_u32_e32 v134, s69, v0
	s_add_u32 s7, s36, 0x100
	v_mov_b32_e32 v0, 0
	v_mov_b32_e32 v133, v173
	v_mov_b32_e32 v129, v173
	v_mov_b32_e32 v131, v173
	s_addc_u32 s9, s37, 0
	s_mov_b32 s85, -2
	v_add_u32_e32 v135, 0, v1
	v_mov_b32_e32 v1, v0
	v_mov_b32_e32 v2, v0
	v_mov_b32_e32 v3, v0
	v_mov_b32_e32 v4, v0
	v_mov_b32_e32 v5, v0
	v_mov_b32_e32 v6, v0
	v_mov_b32_e32 v7, v0
	v_mov_b32_e32 v12, v0
	v_mov_b32_e32 v13, v0
	v_mov_b32_e32 v14, v0
	v_mov_b32_e32 v15, v0
	v_mov_b32_e32 v20, v0
	v_mov_b32_e32 v21, v0
	v_mov_b32_e32 v22, v0
	v_mov_b32_e32 v23, v0
	v_mov_b32_e32 v28, v0
	v_mov_b32_e32 v29, v0
	v_mov_b32_e32 v30, v0
	v_mov_b32_e32 v31, v0
	v_mov_b32_e32 v36, v0
	v_mov_b32_e32 v37, v0
	v_mov_b32_e32 v38, v0
	v_mov_b32_e32 v39, v0
	v_mov_b32_e32 v44, v0
	v_mov_b32_e32 v45, v0
	v_mov_b32_e32 v46, v0
	v_mov_b32_e32 v47, v0
	v_mov_b32_e32 v52, v0
	v_mov_b32_e32 v53, v0
	v_mov_b32_e32 v54, v0
	v_mov_b32_e32 v55, v0
	v_mov_b32_e32 v8, v0
	v_mov_b32_e32 v9, v0
	v_mov_b32_e32 v10, v0
	v_mov_b32_e32 v11, v0
	v_mov_b32_e32 v16, v0
	v_mov_b32_e32 v17, v0
	v_mov_b32_e32 v18, v0
	v_mov_b32_e32 v19, v0
	v_mov_b32_e32 v24, v0
	v_mov_b32_e32 v25, v0
	v_mov_b32_e32 v26, v0
	v_mov_b32_e32 v27, v0
	v_mov_b32_e32 v32, v0
	v_mov_b32_e32 v33, v0
	v_mov_b32_e32 v34, v0
	v_mov_b32_e32 v35, v0
	v_mov_b32_e32 v40, v0
	v_mov_b32_e32 v41, v0
	v_mov_b32_e32 v42, v0
	v_mov_b32_e32 v43, v0
	v_mov_b32_e32 v48, v0
	v_mov_b32_e32 v49, v0
	v_mov_b32_e32 v50, v0
	v_mov_b32_e32 v51, v0
	v_mov_b32_e32 v56, v0
	v_mov_b32_e32 v57, v0
	v_mov_b32_e32 v58, v0
	v_mov_b32_e32 v59, v0
	v_mov_b32_e32 v60, v0
	v_mov_b32_e32 v61, v0
	v_mov_b32_e32 v62, v0
	v_mov_b32_e32 v63, v0
	v_mov_b32_e32 v64, v0
	v_mov_b32_e32 v65, v0
	v_mov_b32_e32 v66, v0
	v_mov_b32_e32 v67, v0
	v_mov_b32_e32 v68, v0
	v_mov_b32_e32 v69, v0
	v_mov_b32_e32 v70, v0
	v_mov_b32_e32 v71, v0
	v_mov_b32_e32 v76, v0
	v_mov_b32_e32 v77, v0
	v_mov_b32_e32 v78, v0
	v_mov_b32_e32 v79, v0
	v_mov_b32_e32 v84, v0
	v_mov_b32_e32 v85, v0
	v_mov_b32_e32 v86, v0
	v_mov_b32_e32 v87, v0
	v_mov_b32_e32 v92, v0
	v_mov_b32_e32 v93, v0
	v_mov_b32_e32 v94, v0
	v_mov_b32_e32 v95, v0
	v_mov_b32_e32 v100, v0
	v_mov_b32_e32 v101, v0
	v_mov_b32_e32 v102, v0
	v_mov_b32_e32 v103, v0
	v_mov_b32_e32 v108, v0
	v_mov_b32_e32 v109, v0
	v_mov_b32_e32 v110, v0
	v_mov_b32_e32 v111, v0
	v_mov_b32_e32 v116, v0
	v_mov_b32_e32 v117, v0
	v_mov_b32_e32 v118, v0
	v_mov_b32_e32 v119, v0
	v_mov_b32_e32 v72, v0
	v_mov_b32_e32 v73, v0
	v_mov_b32_e32 v74, v0
	v_mov_b32_e32 v75, v0
	v_mov_b32_e32 v80, v0
	v_mov_b32_e32 v81, v0
	v_mov_b32_e32 v82, v0
	v_mov_b32_e32 v83, v0
	v_mov_b32_e32 v88, v0
	v_mov_b32_e32 v89, v0
	v_mov_b32_e32 v90, v0
	v_mov_b32_e32 v91, v0
	v_mov_b32_e32 v96, v0
	v_mov_b32_e32 v97, v0
	v_mov_b32_e32 v98, v0
	v_mov_b32_e32 v99, v0
	v_mov_b32_e32 v104, v0
	v_mov_b32_e32 v105, v0
	v_mov_b32_e32 v106, v0
	v_mov_b32_e32 v107, v0
	v_mov_b32_e32 v112, v0
	v_mov_b32_e32 v113, v0
	v_mov_b32_e32 v114, v0
	v_mov_b32_e32 v115, v0
	v_mov_b32_e32 v120, v0
	v_mov_b32_e32 v121, v0
	v_mov_b32_e32 v122, v0
	v_mov_b32_e32 v123, v0
	v_mov_b32_e32 v124, v0
	v_mov_b32_e32 v125, v0
	v_mov_b32_e32 v126, v0
	v_mov_b32_e32 v127, v0
	s_add_u32 s36, s34, 0xfffc0080
	s_addc_u32 s37, s35, -1
	s_add_i32 s87, 0, 0x10000
	s_cmp_eq_u32 s85, 12
	s_cselect_b32 s39, s29, s37
	s_cselect_b32 s38, s28, s36
	s_cselect_b32 s37, s31, s9
	s_cselect_b32 s36, s30, s7
	s_add_i32 s93, 0, 0x14000
.LBB0_671:
	v_add_u32_e32 v148, s87, v134
	v_add_u32_e32 v164, s93, v134
	ds_read_b128 v[136:139], v148
	ds_read_b128 v[140:143], v148 offset:1024
	ds_read_b128 v[144:147], v148 offset:2048
	ds_read_b128 v[148:151], v148 offset:3072
	ds_read_b128 v[152:155], v164
	ds_read_b128 v[156:159], v164 offset:1024
	ds_read_b128 v[160:163], v164 offset:2048
	ds_read_b128 v[164:167], v164 offset:3072
	v_lshl_add_u64 v[174:175], s[34:35], 0, v[172:173]
	s_add_i32 m0, s62, 0xc000
	ds_read_b128 v[168:171], v135
	ds_read_b128 v[188:191], v135 offset:1024
	ds_read_b128 v[204:207], v135 offset:2048
	ds_read_b128 v[208:211], v135 offset:3072
	ds_read_b128 v[212:215], v135 offset:4096
	ds_read_b128 v[216:219], v135 offset:5120
	ds_read_b128 v[220:223], v135 offset:6144
	ds_read_b128 v[224:227], v135 offset:7168
	global_load_lds_dwordx4 v[174:175], off
	v_lshl_add_u64 v[174:175], s[34:35], 0, v[132:133]
	s_add_i32 m0, s62, 0xe000
	s_nop 0
	global_load_lds_dwordx4 v[174:175], off
	s_waitcnt vmcnt(8)
	s_waitcnt lgkmcnt(0)
	s_barrier
	s_setprio 1
	s_waitcnt lgkmcnt(0)
	v_mfma_f32_16x16x32_bf16 v[124:127], v[136:139], v[168:171], v[124:127]
	v_mfma_f32_16x16x32_bf16 v[120:123], v[144:147], v[168:171], v[120:123]
	v_mfma_f32_16x16x32_bf16 v[112:115], v[136:139], v[204:207], v[112:115]
	v_mfma_f32_16x16x32_bf16 v[104:107], v[144:147], v[204:207], v[104:107]
	v_mfma_f32_16x16x32_bf16 v[96:99], v[136:139], v[212:215], v[96:99]
	v_mfma_f32_16x16x32_bf16 v[88:91], v[144:147], v[212:215], v[88:91]
	v_mfma_f32_16x16x32_bf16 v[80:83], v[136:139], v[220:223], v[80:83]
	v_mfma_f32_16x16x32_bf16 v[72:75], v[144:147], v[220:223], v[72:75]
	v_mfma_f32_16x16x32_bf16 v[124:127], v[140:143], v[188:191], v[124:127]
	v_mfma_f32_16x16x32_bf16 v[120:123], v[148:151], v[188:191], v[120:123]
	v_mfma_f32_16x16x32_bf16 v[112:115], v[140:143], v[208:211], v[112:115]
	v_mfma_f32_16x16x32_bf16 v[104:107], v[148:151], v[208:211], v[104:107]
	v_mfma_f32_16x16x32_bf16 v[96:99], v[140:143], v[216:219], v[96:99]
	v_mfma_f32_16x16x32_bf16 v[88:91], v[148:151], v[216:219], v[88:91]
	v_mfma_f32_16x16x32_bf16 v[80:83], v[140:143], v[224:227], v[80:83]
	v_mfma_f32_16x16x32_bf16 v[72:75], v[148:151], v[224:227], v[72:75]
	s_setprio 0
	s_setprio 1
	v_mfma_f32_16x16x32_bf16 v[116:119], v[152:155], v[168:171], v[116:119]
	v_mfma_f32_16x16x32_bf16 v[108:111], v[160:163], v[168:171], v[108:111]
	v_mfma_f32_16x16x32_bf16 v[100:103], v[152:155], v[204:207], v[100:103]
	v_mfma_f32_16x16x32_bf16 v[92:95], v[160:163], v[204:207], v[92:95]
	v_mfma_f32_16x16x32_bf16 v[84:87], v[152:155], v[212:215], v[84:87]
	v_mfma_f32_16x16x32_bf16 v[76:79], v[160:163], v[212:215], v[76:79]
	v_mfma_f32_16x16x32_bf16 v[68:71], v[152:155], v[220:223], v[68:71]
	v_mfma_f32_16x16x32_bf16 v[64:67], v[160:163], v[220:223], v[64:67]
	v_mfma_f32_16x16x32_bf16 v[116:119], v[156:159], v[188:191], v[116:119]
	v_mfma_f32_16x16x32_bf16 v[108:111], v[164:167], v[188:191], v[108:111]
	v_mfma_f32_16x16x32_bf16 v[100:103], v[156:159], v[208:211], v[100:103]
	v_mfma_f32_16x16x32_bf16 v[92:95], v[164:167], v[208:211], v[92:95]
	v_mfma_f32_16x16x32_bf16 v[84:87], v[156:159], v[216:219], v[84:87]
	v_mfma_f32_16x16x32_bf16 v[76:79], v[164:167], v[216:219], v[76:79]
	v_mfma_f32_16x16x32_bf16 v[68:71], v[156:159], v[224:227], v[68:71]
	v_mfma_f32_16x16x32_bf16 v[64:67], v[164:167], v[224:227], v[64:67]
	s_setprio 0
	s_barrier
	s_add_i32 s87, s87, s61
	v_lshl_add_u64 v[174:175], s[36:37], 0, v[128:129]
	s_mov_b32 m0, s87
	ds_read_b128 v[168:171], v135 offset:16384
	ds_read_b128 v[188:191], v135 offset:17408
	ds_read_b128 v[204:207], v135 offset:18432
	ds_read_b128 v[208:211], v135 offset:19456
	ds_read_b128 v[212:215], v135 offset:20480
	ds_read_b128 v[216:219], v135 offset:21504
	ds_read_b128 v[220:223], v135 offset:22528
	ds_read_b128 v[224:227], v135 offset:23552
	global_load_lds_dwordx4 v[174:175], off
	s_add_i32 m0, s87, 0x2000
	s_add_u32 s88, s36, 0x40000
	v_lshl_add_u64 v[176:177], s[36:37], 0, v[130:131]
	s_addc_u32 s89, s37, 0
	s_add_i32 s87, s93, s61
	global_load_lds_dwordx4 v[176:177], off
	v_lshl_add_u64 v[180:181], s[88:89], 0, v[128:129]
	s_mov_b32 m0, s87
	v_lshl_add_u64 v[182:183], s[38:39], 0, v[132:133]
	global_load_lds_dwordx4 v[180:181], off
	v_lshl_add_u64 v[180:181], s[88:89], 0, v[130:131]
	s_add_i32 m0, s87, 0x2000
	s_nop 0
	global_load_lds_dwordx4 v[180:181], off
	v_lshl_add_u64 v[180:181], s[38:39], 0, v[172:173]
	s_mov_b32 m0, s62
	s_nop 0
	global_load_lds_dwordx4 v[180:181], off
	s_mov_b32 m0, s63
	s_nop 0
	global_load_lds_dwordx4 v[182:183], off
	s_waitcnt vmcnt(8)
	s_waitcnt lgkmcnt(0)
	s_barrier
	s_setprio 1
	s_waitcnt lgkmcnt(0)
	v_mfma_f32_16x16x32_bf16 v[60:63], v[136:139], v[168:171], v[60:63]
	v_mfma_f32_16x16x32_bf16 v[56:59], v[144:147], v[168:171], v[56:59]
	v_mfma_f32_16x16x32_bf16 v[48:51], v[136:139], v[204:207], v[48:51]
	v_mfma_f32_16x16x32_bf16 v[40:43], v[144:147], v[204:207], v[40:43]
	v_mfma_f32_16x16x32_bf16 v[32:35], v[136:139], v[212:215], v[32:35]
	v_mfma_f32_16x16x32_bf16 v[24:27], v[144:147], v[212:215], v[24:27]
	v_mfma_f32_16x16x32_bf16 v[16:19], v[136:139], v[220:223], v[16:19]
	v_mfma_f32_16x16x32_bf16 v[8:11], v[144:147], v[220:223], v[8:11]
	v_mfma_f32_16x16x32_bf16 v[60:63], v[140:143], v[188:191], v[60:63]
	v_mfma_f32_16x16x32_bf16 v[56:59], v[148:151], v[188:191], v[56:59]
	v_mfma_f32_16x16x32_bf16 v[48:51], v[140:143], v[208:211], v[48:51]
	v_mfma_f32_16x16x32_bf16 v[40:43], v[148:151], v[208:211], v[40:43]
	v_mfma_f32_16x16x32_bf16 v[32:35], v[140:143], v[216:219], v[32:35]
	v_mfma_f32_16x16x32_bf16 v[24:27], v[148:151], v[216:219], v[24:27]
	v_mfma_f32_16x16x32_bf16 v[16:19], v[140:143], v[224:227], v[16:19]
	v_mfma_f32_16x16x32_bf16 v[8:11], v[148:151], v[224:227], v[8:11]
	s_setprio 0
	s_setprio 1
	v_mfma_f32_16x16x32_bf16 v[52:55], v[152:155], v[168:171], v[52:55]
	v_mfma_f32_16x16x32_bf16 v[44:47], v[160:163], v[168:171], v[44:47]
	v_mfma_f32_16x16x32_bf16 v[36:39], v[152:155], v[204:207], v[36:39]
	v_mfma_f32_16x16x32_bf16 v[28:31], v[160:163], v[204:207], v[28:31]
	v_mfma_f32_16x16x32_bf16 v[20:23], v[152:155], v[212:215], v[20:23]
	v_mfma_f32_16x16x32_bf16 v[12:15], v[160:163], v[212:215], v[12:15]
	v_mfma_f32_16x16x32_bf16 v[4:7], v[152:155], v[220:223], v[4:7]
	v_mfma_f32_16x16x32_bf16 v[0:3], v[160:163], v[220:223], v[0:3]
	v_mfma_f32_16x16x32_bf16 v[52:55], v[156:159], v[188:191], v[52:55]
	v_mfma_f32_16x16x32_bf16 v[44:47], v[164:167], v[188:191], v[44:47]
	v_mfma_f32_16x16x32_bf16 v[36:39], v[156:159], v[208:211], v[36:39]
	v_mfma_f32_16x16x32_bf16 v[28:31], v[164:167], v[208:211], v[28:31]
	v_mfma_f32_16x16x32_bf16 v[20:23], v[156:159], v[216:219], v[20:23]
	v_mfma_f32_16x16x32_bf16 v[12:15], v[164:167], v[216:219], v[12:15]
	v_mfma_f32_16x16x32_bf16 v[4:7], v[156:159], v[224:227], v[4:7]
	v_mfma_f32_16x16x32_bf16 v[0:3], v[164:167], v[224:227], v[0:3]
	s_setprio 0
	s_barrier
	s_add_i32 s87, 0, 0x18000
	s_add_i32 s88, 0, 0x1c000
	v_add_u32_e32 v148, s87, v134
	v_add_u32_e32 v164, s88, v134
	ds_read_b128 v[136:139], v148
	ds_read_b128 v[140:143], v148 offset:1024
	ds_read_b128 v[144:147], v148 offset:2048
	ds_read_b128 v[148:151], v148 offset:3072
	ds_read_b128 v[152:155], v164
	ds_read_b128 v[156:159], v164 offset:1024
	ds_read_b128 v[160:163], v164 offset:2048
	ds_read_b128 v[164:167], v164 offset:3072
	s_add_u32 s38, s38, 0x40000
	s_addc_u32 s39, s39, 0
	s_mov_b32 m0, s64
	v_lshl_add_u64 v[228:229], s[38:39], 0, v[172:173]
	ds_read_b128 v[168:171], v135 offset:32768
	ds_read_b128 v[188:191], v135 offset:33792
	ds_read_b128 v[204:207], v135 offset:34816
	ds_read_b128 v[208:211], v135 offset:35840
	ds_read_b128 v[212:215], v135 offset:36864
	ds_read_b128 v[216:219], v135 offset:37888
	ds_read_b128 v[220:223], v135 offset:38912
	ds_read_b128 v[224:227], v135 offset:39936
	global_load_lds_dwordx4 v[228:229], off
	v_lshl_add_u64 v[228:229], s[38:39], 0, v[132:133]
	s_mov_b32 m0, s65
	s_nop 0
	global_load_lds_dwordx4 v[228:229], off
	s_waitcnt vmcnt(8)
	s_waitcnt lgkmcnt(0)
	s_barrier
	s_setprio 1
	s_waitcnt lgkmcnt(0)
	v_mfma_f32_16x16x32_bf16 v[124:127], v[136:139], v[168:171], v[124:127]
	v_mfma_f32_16x16x32_bf16 v[120:123], v[144:147], v[168:171], v[120:123]
	v_mfma_f32_16x16x32_bf16 v[112:115], v[136:139], v[204:207], v[112:115]
	v_mfma_f32_16x16x32_bf16 v[104:107], v[144:147], v[204:207], v[104:107]
	v_mfma_f32_16x16x32_bf16 v[96:99], v[136:139], v[212:215], v[96:99]
	v_mfma_f32_16x16x32_bf16 v[88:91], v[144:147], v[212:215], v[88:91]
	v_mfma_f32_16x16x32_bf16 v[80:83], v[136:139], v[220:223], v[80:83]
	v_mfma_f32_16x16x32_bf16 v[72:75], v[144:147], v[220:223], v[72:75]
	v_mfma_f32_16x16x32_bf16 v[124:127], v[140:143], v[188:191], v[124:127]
	v_mfma_f32_16x16x32_bf16 v[120:123], v[148:151], v[188:191], v[120:123]
	v_mfma_f32_16x16x32_bf16 v[112:115], v[140:143], v[208:211], v[112:115]
	v_mfma_f32_16x16x32_bf16 v[104:107], v[148:151], v[208:211], v[104:107]
	v_mfma_f32_16x16x32_bf16 v[96:99], v[140:143], v[216:219], v[96:99]
	v_mfma_f32_16x16x32_bf16 v[88:91], v[148:151], v[216:219], v[88:91]
	v_mfma_f32_16x16x32_bf16 v[80:83], v[140:143], v[224:227], v[80:83]
	v_mfma_f32_16x16x32_bf16 v[72:75], v[148:151], v[224:227], v[72:75]
	s_setprio 0
	s_setprio 1
	v_mfma_f32_16x16x32_bf16 v[116:119], v[152:155], v[168:171], v[116:119]
	v_mfma_f32_16x16x32_bf16 v[108:111], v[160:163], v[168:171], v[108:111]
	v_mfma_f32_16x16x32_bf16 v[100:103], v[152:155], v[204:207], v[100:103]
	v_mfma_f32_16x16x32_bf16 v[92:95], v[160:163], v[204:207], v[92:95]
	v_mfma_f32_16x16x32_bf16 v[84:87], v[152:155], v[212:215], v[84:87]
	v_mfma_f32_16x16x32_bf16 v[76:79], v[160:163], v[212:215], v[76:79]
	v_mfma_f32_16x16x32_bf16 v[68:71], v[152:155], v[220:223], v[68:71]
	v_mfma_f32_16x16x32_bf16 v[64:67], v[160:163], v[220:223], v[64:67]
	v_mfma_f32_16x16x32_bf16 v[116:119], v[156:159], v[188:191], v[116:119]
	v_mfma_f32_16x16x32_bf16 v[108:111], v[164:167], v[188:191], v[108:111]
	v_mfma_f32_16x16x32_bf16 v[100:103], v[156:159], v[208:211], v[100:103]
	v_mfma_f32_16x16x32_bf16 v[92:95], v[164:167], v[208:211], v[92:95]
	v_mfma_f32_16x16x32_bf16 v[84:87], v[156:159], v[216:219], v[84:87]
	v_mfma_f32_16x16x32_bf16 v[76:79], v[164:167], v[216:219], v[76:79]
	v_mfma_f32_16x16x32_bf16 v[68:71], v[156:159], v[224:227], v[68:71]
	v_mfma_f32_16x16x32_bf16 v[64:67], v[164:167], v[224:227], v[64:67]
	s_setprio 0
	s_barrier
	s_add_i32 s38, s87, s61
	v_lshl_add_u64 v[174:175], v[174:175], 0, s[94:95]
	s_mov_b32 m0, s38
	ds_read_b128 v[168:171], v135 offset:49152
	ds_read_b128 v[188:191], v135 offset:50176
	ds_read_b128 v[204:207], v135 offset:51200
	ds_read_b128 v[208:211], v135 offset:52224
	ds_read_b128 v[212:215], v135 offset:53248
	ds_read_b128 v[216:219], v135 offset:54272
	ds_read_b128 v[220:223], v135 offset:55296
	ds_read_b128 v[224:227], v135 offset:56320
	global_load_lds_dwordx4 v[174:175], off
	s_add_i32 m0, s38, 0x2000
	s_add_u32 s36, s36, 0x40080
	v_lshl_add_u64 v[174:175], v[176:177], 0, s[94:95]
	s_addc_u32 s37, s37, 0
	s_add_i32 s38, s88, s61
	global_load_lds_dwordx4 v[174:175], off
	v_lshl_add_u64 v[174:175], s[36:37], 0, v[128:129]
	s_mov_b32 m0, s38
	s_nop 0
	global_load_lds_dwordx4 v[174:175], off
	v_lshl_add_u64 v[174:175], s[36:37], 0, v[130:131]
	s_add_i32 m0, s38, 0x2000
	s_nop 0
	global_load_lds_dwordx4 v[174:175], off
	v_lshl_add_u64 v[174:175], v[180:181], 0, s[94:95]
	s_mov_b32 m0, s70
	s_nop 0
	global_load_lds_dwordx4 v[174:175], off
	v_lshl_add_u64 v[174:175], v[182:183], 0, s[94:95]
	s_mov_b32 m0, s71
	s_nop 0
	global_load_lds_dwordx4 v[174:175], off
	s_waitcnt vmcnt(8)
	s_waitcnt lgkmcnt(0)
	s_barrier
	s_setprio 1
	s_waitcnt lgkmcnt(0)
	v_mfma_f32_16x16x32_bf16 v[60:63], v[136:139], v[168:171], v[60:63]
	v_mfma_f32_16x16x32_bf16 v[56:59], v[144:147], v[168:171], v[56:59]
	v_mfma_f32_16x16x32_bf16 v[48:51], v[136:139], v[204:207], v[48:51]
	v_mfma_f32_16x16x32_bf16 v[40:43], v[144:147], v[204:207], v[40:43]
	v_mfma_f32_16x16x32_bf16 v[32:35], v[136:139], v[212:215], v[32:35]
	v_mfma_f32_16x16x32_bf16 v[24:27], v[144:147], v[212:215], v[24:27]
	v_mfma_f32_16x16x32_bf16 v[16:19], v[136:139], v[220:223], v[16:19]
	v_mfma_f32_16x16x32_bf16 v[8:11], v[144:147], v[220:223], v[8:11]
	v_mfma_f32_16x16x32_bf16 v[60:63], v[140:143], v[188:191], v[60:63]
	v_mfma_f32_16x16x32_bf16 v[56:59], v[148:151], v[188:191], v[56:59]
	v_mfma_f32_16x16x32_bf16 v[48:51], v[140:143], v[208:211], v[48:51]
	v_mfma_f32_16x16x32_bf16 v[40:43], v[148:151], v[208:211], v[40:43]
	v_mfma_f32_16x16x32_bf16 v[32:35], v[140:143], v[216:219], v[32:35]
	v_mfma_f32_16x16x32_bf16 v[24:27], v[148:151], v[216:219], v[24:27]
	v_mfma_f32_16x16x32_bf16 v[16:19], v[140:143], v[224:227], v[16:19]
	v_mfma_f32_16x16x32_bf16 v[8:11], v[148:151], v[224:227], v[8:11]
	s_setprio 0
	s_setprio 1
	v_mfma_f32_16x16x32_bf16 v[52:55], v[152:155], v[168:171], v[52:55]
	v_mfma_f32_16x16x32_bf16 v[44:47], v[160:163], v[168:171], v[44:47]
	v_mfma_f32_16x16x32_bf16 v[36:39], v[152:155], v[204:207], v[36:39]
	v_mfma_f32_16x16x32_bf16 v[28:31], v[160:163], v[204:207], v[28:31]
	v_mfma_f32_16x16x32_bf16 v[20:23], v[152:155], v[212:215], v[20:23]
	v_mfma_f32_16x16x32_bf16 v[12:15], v[160:163], v[212:215], v[12:15]
	v_mfma_f32_16x16x32_bf16 v[4:7], v[152:155], v[220:223], v[4:7]
	v_mfma_f32_16x16x32_bf16 v[0:3], v[160:163], v[220:223], v[0:3]
	v_mfma_f32_16x16x32_bf16 v[52:55], v[156:159], v[188:191], v[52:55]
	v_mfma_f32_16x16x32_bf16 v[44:47], v[164:167], v[188:191], v[44:47]
	v_mfma_f32_16x16x32_bf16 v[36:39], v[156:159], v[208:211], v[36:39]
	v_mfma_f32_16x16x32_bf16 v[28:31], v[164:167], v[208:211], v[28:31]
	v_mfma_f32_16x16x32_bf16 v[20:23], v[156:159], v[216:219], v[20:23]
	v_mfma_f32_16x16x32_bf16 v[12:15], v[164:167], v[216:219], v[12:15]
	v_mfma_f32_16x16x32_bf16 v[4:7], v[156:159], v[224:227], v[4:7]
	v_mfma_f32_16x16x32_bf16 v[0:3], v[164:167], v[224:227], v[0:3]
	s_setprio 0
	s_add_i32 s85, s85, 2
	s_add_u32 s34, s34, 0x100
	s_addc_u32 s35, s35, 0
	s_add_u32 s7, s7, 0x100
	s_addc_u32 s9, s9, 0
	s_cmp_gt_u32 s85, 13
	s_cbranch_scc1 .Lkrot2_exit
	s_add_u32 s36, s34, 0xfffc0080
	s_addc_u32 s37, s35, -1
	s_add_i32 s87, 0, 0x10000
	s_cmp_eq_u32 s85, 12
	s_cselect_b32 s39, s29, s37
	s_cselect_b32 s38, s28, s36
	s_cselect_b32 s37, s31, s9
	s_cselect_b32 s36, s30, s7
	s_add_i32 s93, 0, 0x14000
	s_barrier
	s_branch .LBB0_671
.Lkrot2_exit:
	s_barrier
	s_and_b64 vcc, exec, s[26:27]
	s_cbranch_vccz .LBB0_674
	s_barrier

.LBB0_746:
	s_add_u32 s22, s22, 0x40080
	s_addc_u32 s23, s23, 0
	v_add_u32_e32 v1, s39, v1
	v_add_u32_e32 v134, s45, v0
	s_add_u32 s15, s24, 0x100
	v_mov_b32_e32 v0, 0
	v_mov_b32_e32 v131, v173
	v_mov_b32_e32 v129, v173
	v_mov_b32_e32 v133, v173
	s_addc_u32 s17, s25, 0
	s_mov_b32 s61, -2
	v_add_u32_e32 v135, 0, v1
	v_mov_b32_e32 v1, v0
	v_mov_b32_e32 v2, v0
	v_mov_b32_e32 v3, v0
	v_mov_b32_e32 v4, v0
	v_mov_b32_e32 v5, v0
	v_mov_b32_e32 v6, v0
	v_mov_b32_e32 v7, v0
	v_mov_b32_e32 v12, v0
	v_mov_b32_e32 v13, v0
	v_mov_b32_e32 v14, v0
	v_mov_b32_e32 v15, v0
	v_mov_b32_e32 v20, v0
	v_mov_b32_e32 v21, v0
	v_mov_b32_e32 v22, v0
	v_mov_b32_e32 v23, v0
	v_mov_b32_e32 v28, v0
	v_mov_b32_e32 v29, v0
	v_mov_b32_e32 v30, v0
	v_mov_b32_e32 v31, v0
	v_mov_b32_e32 v36, v0
	v_mov_b32_e32 v37, v0
	v_mov_b32_e32 v38, v0
	v_mov_b32_e32 v39, v0
	v_mov_b32_e32 v44, v0
	v_mov_b32_e32 v45, v0
	v_mov_b32_e32 v46, v0
	v_mov_b32_e32 v47, v0
	v_mov_b32_e32 v52, v0
	v_mov_b32_e32 v53, v0
	v_mov_b32_e32 v54, v0
	v_mov_b32_e32 v55, v0
	v_mov_b32_e32 v8, v0
	v_mov_b32_e32 v9, v0
	v_mov_b32_e32 v10, v0
	v_mov_b32_e32 v11, v0
	v_mov_b32_e32 v16, v0
	v_mov_b32_e32 v17, v0
	v_mov_b32_e32 v18, v0
	v_mov_b32_e32 v19, v0
	v_mov_b32_e32 v24, v0
	v_mov_b32_e32 v25, v0
	v_mov_b32_e32 v26, v0
	v_mov_b32_e32 v27, v0
	v_mov_b32_e32 v32, v0
	v_mov_b32_e32 v33, v0
	v_mov_b32_e32 v34, v0
	v_mov_b32_e32 v35, v0
	v_mov_b32_e32 v40, v0
	v_mov_b32_e32 v41, v0
	v_mov_b32_e32 v42, v0
	v_mov_b32_e32 v43, v0
	v_mov_b32_e32 v48, v0
	v_mov_b32_e32 v49, v0
	v_mov_b32_e32 v50, v0
	v_mov_b32_e32 v51, v0
	v_mov_b32_e32 v56, v0
	v_mov_b32_e32 v57, v0
	v_mov_b32_e32 v58, v0
	v_mov_b32_e32 v59, v0
	v_mov_b32_e32 v60, v0
	v_mov_b32_e32 v61, v0
	v_mov_b32_e32 v62, v0
	v_mov_b32_e32 v63, v0
	v_mov_b32_e32 v64, v0
	v_mov_b32_e32 v65, v0
	v_mov_b32_e32 v66, v0
	v_mov_b32_e32 v67, v0
	v_mov_b32_e32 v68, v0
	v_mov_b32_e32 v69, v0
	v_mov_b32_e32 v70, v0
	v_mov_b32_e32 v71, v0
	v_mov_b32_e32 v76, v0
	v_mov_b32_e32 v77, v0
	v_mov_b32_e32 v78, v0
	v_mov_b32_e32 v79, v0
	v_mov_b32_e32 v84, v0
	v_mov_b32_e32 v85, v0
	v_mov_b32_e32 v86, v0
	v_mov_b32_e32 v87, v0
	v_mov_b32_e32 v92, v0
	v_mov_b32_e32 v93, v0
	v_mov_b32_e32 v94, v0
	v_mov_b32_e32 v95, v0
	v_mov_b32_e32 v100, v0
	v_mov_b32_e32 v101, v0
	v_mov_b32_e32 v102, v0
	v_mov_b32_e32 v103, v0
	v_mov_b32_e32 v108, v0
	v_mov_b32_e32 v109, v0
	v_mov_b32_e32 v110, v0
	v_mov_b32_e32 v111, v0
	v_mov_b32_e32 v116, v0
	v_mov_b32_e32 v117, v0
	v_mov_b32_e32 v118, v0
	v_mov_b32_e32 v119, v0
	v_mov_b32_e32 v72, v0
	v_mov_b32_e32 v73, v0
	v_mov_b32_e32 v74, v0
	v_mov_b32_e32 v75, v0
	v_mov_b32_e32 v80, v0
	v_mov_b32_e32 v81, v0
	v_mov_b32_e32 v82, v0
	v_mov_b32_e32 v83, v0
	v_mov_b32_e32 v88, v0
	v_mov_b32_e32 v89, v0
	v_mov_b32_e32 v90, v0
	v_mov_b32_e32 v91, v0
	v_mov_b32_e32 v96, v0
	v_mov_b32_e32 v97, v0
	v_mov_b32_e32 v98, v0
	v_mov_b32_e32 v99, v0
	v_mov_b32_e32 v104, v0
	v_mov_b32_e32 v105, v0
	v_mov_b32_e32 v106, v0
	v_mov_b32_e32 v107, v0
	v_mov_b32_e32 v112, v0
	v_mov_b32_e32 v113, v0
	v_mov_b32_e32 v114, v0
	v_mov_b32_e32 v115, v0
	v_mov_b32_e32 v120, v0
	v_mov_b32_e32 v121, v0
	v_mov_b32_e32 v122, v0
	v_mov_b32_e32 v123, v0
	v_mov_b32_e32 v124, v0
	v_mov_b32_e32 v125, v0
	v_mov_b32_e32 v126, v0
	v_mov_b32_e32 v127, v0
	s_add_u32 s24, s22, 0xfffc0080
	s_addc_u32 s25, s23, -1
	s_add_i32 s62, 0, 0x10000
	s_cmp_eq_u32 s61, 12
	s_cselect_b32 s27, s19, s25
	s_cselect_b32 s26, s18, s24
	s_cselect_b32 s25, s21, s17
	s_cselect_b32 s24, s20, s15
	s_add_i32 s64, 0, 0x14000
.LBB0_747:
	v_add_u32_e32 v148, s62, v134
	v_add_u32_e32 v164, s64, v134
	ds_read_b128 v[136:139], v148
	ds_read_b128 v[140:143], v148 offset:1024
	ds_read_b128 v[144:147], v148 offset:2048
	ds_read_b128 v[148:151], v148 offset:3072
	ds_read_b128 v[152:155], v164
	ds_read_b128 v[156:159], v164 offset:1024
	ds_read_b128 v[160:163], v164 offset:2048
	ds_read_b128 v[164:167], v164 offset:3072
	v_lshl_add_u64 v[174:175], s[22:23], 0, v[172:173]
	s_add_i32 m0, s34, 0xc000
	ds_read_b128 v[168:171], v135
	ds_read_b128 v[188:191], v135 offset:1024
	ds_read_b128 v[204:207], v135 offset:2048
	ds_read_b128 v[208:211], v135 offset:3072
	ds_read_b128 v[212:215], v135 offset:4096
	ds_read_b128 v[216:219], v135 offset:5120
	ds_read_b128 v[220:223], v135 offset:6144
	ds_read_b128 v[224:227], v135 offset:7168
	global_load_lds_dwordx4 v[174:175], off
	v_lshl_add_u64 v[174:175], s[22:23], 0, v[130:131]
	s_add_i32 m0, s34, 0xe000
	s_nop 0
	global_load_lds_dwordx4 v[174:175], off
	s_waitcnt vmcnt(8)
	s_waitcnt lgkmcnt(0)
	s_barrier
	s_setprio 1
	s_waitcnt lgkmcnt(0)
	v_mfma_f32_16x16x32_bf16 v[124:127], v[136:139], v[168:171], v[124:127]
	v_mfma_f32_16x16x32_bf16 v[120:123], v[144:147], v[168:171], v[120:123]
	v_mfma_f32_16x16x32_bf16 v[112:115], v[136:139], v[204:207], v[112:115]
	v_mfma_f32_16x16x32_bf16 v[104:107], v[144:147], v[204:207], v[104:107]
	v_mfma_f32_16x16x32_bf16 v[96:99], v[136:139], v[212:215], v[96:99]
	v_mfma_f32_16x16x32_bf16 v[88:91], v[144:147], v[212:215], v[88:91]
	v_mfma_f32_16x16x32_bf16 v[80:83], v[136:139], v[220:223], v[80:83]
	v_mfma_f32_16x16x32_bf16 v[72:75], v[144:147], v[220:223], v[72:75]
	v_mfma_f32_16x16x32_bf16 v[124:127], v[140:143], v[188:191], v[124:127]
	v_mfma_f32_16x16x32_bf16 v[120:123], v[148:151], v[188:191], v[120:123]
	v_mfma_f32_16x16x32_bf16 v[112:115], v[140:143], v[208:211], v[112:115]
	v_mfma_f32_16x16x32_bf16 v[104:107], v[148:151], v[208:211], v[104:107]
	v_mfma_f32_16x16x32_bf16 v[96:99], v[140:143], v[216:219], v[96:99]
	v_mfma_f32_16x16x32_bf16 v[88:91], v[148:151], v[216:219], v[88:91]
	v_mfma_f32_16x16x32_bf16 v[80:83], v[140:143], v[224:227], v[80:83]
	v_mfma_f32_16x16x32_bf16 v[72:75], v[148:151], v[224:227], v[72:75]
	s_setprio 0
	s_setprio 1
	v_mfma_f32_16x16x32_bf16 v[116:119], v[152:155], v[168:171], v[116:119]
	v_mfma_f32_16x16x32_bf16 v[108:111], v[160:163], v[168:171], v[108:111]
	v_mfma_f32_16x16x32_bf16 v[100:103], v[152:155], v[204:207], v[100:103]
	v_mfma_f32_16x16x32_bf16 v[92:95], v[160:163], v[204:207], v[92:95]
	v_mfma_f32_16x16x32_bf16 v[84:87], v[152:155], v[212:215], v[84:87]
	v_mfma_f32_16x16x32_bf16 v[76:79], v[160:163], v[212:215], v[76:79]
	v_mfma_f32_16x16x32_bf16 v[68:71], v[152:155], v[220:223], v[68:71]
	v_mfma_f32_16x16x32_bf16 v[64:67], v[160:163], v[220:223], v[64:67]
	v_mfma_f32_16x16x32_bf16 v[116:119], v[156:159], v[188:191], v[116:119]
	v_mfma_f32_16x16x32_bf16 v[108:111], v[164:167], v[188:191], v[108:111]
	v_mfma_f32_16x16x32_bf16 v[100:103], v[156:159], v[208:211], v[100:103]
	v_mfma_f32_16x16x32_bf16 v[92:95], v[164:167], v[208:211], v[92:95]
	v_mfma_f32_16x16x32_bf16 v[84:87], v[156:159], v[216:219], v[84:87]
	v_mfma_f32_16x16x32_bf16 v[76:79], v[164:167], v[216:219], v[76:79]
	v_mfma_f32_16x16x32_bf16 v[68:71], v[156:159], v[224:227], v[68:71]
	v_mfma_f32_16x16x32_bf16 v[64:67], v[164:167], v[224:227], v[64:67]
	s_setprio 0
	s_barrier
	s_add_i32 s62, s62, s31
	v_lshl_add_u64 v[174:175], s[24:25], 0, v[128:129]
	s_mov_b32 m0, s62
	ds_read_b128 v[168:171], v135 offset:16384
	ds_read_b128 v[188:191], v135 offset:17408
	ds_read_b128 v[204:207], v135 offset:18432
	ds_read_b128 v[208:211], v135 offset:19456
	ds_read_b128 v[212:215], v135 offset:20480
	ds_read_b128 v[216:219], v135 offset:21504
	ds_read_b128 v[220:223], v135 offset:22528
	ds_read_b128 v[224:227], v135 offset:23552
	global_load_lds_dwordx4 v[174:175], off
	s_add_i32 m0, s62, 0x2000
	s_add_u32 s62, s24, 0x40000
	v_lshl_add_u64 v[176:177], s[24:25], 0, v[132:133]
	s_addc_u32 s63, s25, 0
	s_add_i32 s64, s64, s31
	global_load_lds_dwordx4 v[176:177], off
	v_lshl_add_u64 v[180:181], s[62:63], 0, v[128:129]
	s_mov_b32 m0, s64
	v_lshl_add_u64 v[182:183], s[26:27], 0, v[130:131]
	global_load_lds_dwordx4 v[180:181], off
	v_lshl_add_u64 v[180:181], s[62:63], 0, v[132:133]
	s_add_i32 m0, s64, 0x2000
	s_nop 0
	global_load_lds_dwordx4 v[180:181], off
	v_lshl_add_u64 v[180:181], s[26:27], 0, v[172:173]
	s_mov_b32 m0, s34
	s_nop 0
	global_load_lds_dwordx4 v[180:181], off
	s_mov_b32 m0, s35
	s_nop 0
	global_load_lds_dwordx4 v[182:183], off
	s_waitcnt vmcnt(8)
	s_waitcnt lgkmcnt(0)
	s_barrier
	s_setprio 1
	s_waitcnt lgkmcnt(0)
	v_mfma_f32_16x16x32_bf16 v[60:63], v[136:139], v[168:171], v[60:63]
	v_mfma_f32_16x16x32_bf16 v[56:59], v[144:147], v[168:171], v[56:59]
	v_mfma_f32_16x16x32_bf16 v[48:51], v[136:139], v[204:207], v[48:51]
	v_mfma_f32_16x16x32_bf16 v[40:43], v[144:147], v[204:207], v[40:43]
	v_mfma_f32_16x16x32_bf16 v[32:35], v[136:139], v[212:215], v[32:35]
	v_mfma_f32_16x16x32_bf16 v[24:27], v[144:147], v[212:215], v[24:27]
	v_mfma_f32_16x16x32_bf16 v[16:19], v[136:139], v[220:223], v[16:19]
	v_mfma_f32_16x16x32_bf16 v[8:11], v[144:147], v[220:223], v[8:11]
	v_mfma_f32_16x16x32_bf16 v[60:63], v[140:143], v[188:191], v[60:63]
	v_mfma_f32_16x16x32_bf16 v[56:59], v[148:151], v[188:191], v[56:59]
	v_mfma_f32_16x16x32_bf16 v[48:51], v[140:143], v[208:211], v[48:51]
	v_mfma_f32_16x16x32_bf16 v[40:43], v[148:151], v[208:211], v[40:43]
	v_mfma_f32_16x16x32_bf16 v[32:35], v[140:143], v[216:219], v[32:35]
	v_mfma_f32_16x16x32_bf16 v[24:27], v[148:151], v[216:219], v[24:27]
	v_mfma_f32_16x16x32_bf16 v[16:19], v[140:143], v[224:227], v[16:19]
	v_mfma_f32_16x16x32_bf16 v[8:11], v[148:151], v[224:227], v[8:11]
	s_setprio 0
	s_setprio 1
	v_mfma_f32_16x16x32_bf16 v[52:55], v[152:155], v[168:171], v[52:55]
	v_mfma_f32_16x16x32_bf16 v[44:47], v[160:163], v[168:171], v[44:47]
	v_mfma_f32_16x16x32_bf16 v[36:39], v[152:155], v[204:207], v[36:39]
	v_mfma_f32_16x16x32_bf16 v[28:31], v[160:163], v[204:207], v[28:31]
	v_mfma_f32_16x16x32_bf16 v[20:23], v[152:155], v[212:215], v[20:23]
	v_mfma_f32_16x16x32_bf16 v[12:15], v[160:163], v[212:215], v[12:15]
	v_mfma_f32_16x16x32_bf16 v[4:7], v[152:155], v[220:223], v[4:7]
	v_mfma_f32_16x16x32_bf16 v[0:3], v[160:163], v[220:223], v[0:3]
	v_mfma_f32_16x16x32_bf16 v[52:55], v[156:159], v[188:191], v[52:55]
	v_mfma_f32_16x16x32_bf16 v[44:47], v[164:167], v[188:191], v[44:47]
	v_mfma_f32_16x16x32_bf16 v[36:39], v[156:159], v[208:211], v[36:39]
	v_mfma_f32_16x16x32_bf16 v[28:31], v[164:167], v[208:211], v[28:31]
	v_mfma_f32_16x16x32_bf16 v[20:23], v[156:159], v[216:219], v[20:23]
	v_mfma_f32_16x16x32_bf16 v[12:15], v[164:167], v[216:219], v[12:15]
	v_mfma_f32_16x16x32_bf16 v[4:7], v[156:159], v[224:227], v[4:7]
	v_mfma_f32_16x16x32_bf16 v[0:3], v[164:167], v[224:227], v[0:3]
	s_setprio 0
	s_barrier
	s_add_i32 s62, 0, 0x18000
	s_add_i32 s63, 0, 0x1c000
	v_add_u32_e32 v148, s62, v134
	v_add_u32_e32 v164, s63, v134
	ds_read_b128 v[136:139], v148
	ds_read_b128 v[140:143], v148 offset:1024
	ds_read_b128 v[144:147], v148 offset:2048
	ds_read_b128 v[148:151], v148 offset:3072
	ds_read_b128 v[152:155], v164
	ds_read_b128 v[156:159], v164 offset:1024
	ds_read_b128 v[160:163], v164 offset:2048
	ds_read_b128 v[164:167], v164 offset:3072
	s_add_u32 s26, s26, 0x40000
	s_addc_u32 s27, s27, 0
	s_mov_b32 m0, s36
	v_lshl_add_u64 v[228:229], s[26:27], 0, v[172:173]
	ds_read_b128 v[168:171], v135 offset:32768
	ds_read_b128 v[188:191], v135 offset:33792
	ds_read_b128 v[204:207], v135 offset:34816
	ds_read_b128 v[208:211], v135 offset:35840
	ds_read_b128 v[212:215], v135 offset:36864
	ds_read_b128 v[216:219], v135 offset:37888
	ds_read_b128 v[220:223], v135 offset:38912
	ds_read_b128 v[224:227], v135 offset:39936
	global_load_lds_dwordx4 v[228:229], off
	v_lshl_add_u64 v[228:229], s[26:27], 0, v[130:131]
	s_mov_b32 m0, s37
	s_nop 0
	global_load_lds_dwordx4 v[228:229], off
	s_waitcnt vmcnt(8)
	s_waitcnt lgkmcnt(0)
	s_barrier
	s_setprio 1
	s_waitcnt lgkmcnt(0)
	v_mfma_f32_16x16x32_bf16 v[124:127], v[136:139], v[168:171], v[124:127]
	v_mfma_f32_16x16x32_bf16 v[120:123], v[144:147], v[168:171], v[120:123]
	v_mfma_f32_16x16x32_bf16 v[112:115], v[136:139], v[204:207], v[112:115]
	v_mfma_f32_16x16x32_bf16 v[104:107], v[144:147], v[204:207], v[104:107]
	v_mfma_f32_16x16x32_bf16 v[96:99], v[136:139], v[212:215], v[96:99]
	v_mfma_f32_16x16x32_bf16 v[88:91], v[144:147], v[212:215], v[88:91]
	v_mfma_f32_16x16x32_bf16 v[80:83], v[136:139], v[220:223], v[80:83]
	v_mfma_f32_16x16x32_bf16 v[72:75], v[144:147], v[220:223], v[72:75]
	v_mfma_f32_16x16x32_bf16 v[124:127], v[140:143], v[188:191], v[124:127]
	v_mfma_f32_16x16x32_bf16 v[120:123], v[148:151], v[188:191], v[120:123]
	v_mfma_f32_16x16x32_bf16 v[112:115], v[140:143], v[208:211], v[112:115]
	v_mfma_f32_16x16x32_bf16 v[104:107], v[148:151], v[208:211], v[104:107]
	v_mfma_f32_16x16x32_bf16 v[96:99], v[140:143], v[216:219], v[96:99]
	v_mfma_f32_16x16x32_bf16 v[88:91], v[148:151], v[216:219], v[88:91]
	v_mfma_f32_16x16x32_bf16 v[80:83], v[140:143], v[224:227], v[80:83]
	v_mfma_f32_16x16x32_bf16 v[72:75], v[148:151], v[224:227], v[72:75]
	s_setprio 0
	s_setprio 1
	v_mfma_f32_16x16x32_bf16 v[116:119], v[152:155], v[168:171], v[116:119]
	v_mfma_f32_16x16x32_bf16 v[108:111], v[160:163], v[168:171], v[108:111]
	v_mfma_f32_16x16x32_bf16 v[100:103], v[152:155], v[204:207], v[100:103]
	v_mfma_f32_16x16x32_bf16 v[92:95], v[160:163], v[204:207], v[92:95]
	v_mfma_f32_16x16x32_bf16 v[84:87], v[152:155], v[212:215], v[84:87]
	v_mfma_f32_16x16x32_bf16 v[76:79], v[160:163], v[212:215], v[76:79]
	v_mfma_f32_16x16x32_bf16 v[68:71], v[152:155], v[220:223], v[68:71]
	v_mfma_f32_16x16x32_bf16 v[64:67], v[160:163], v[220:223], v[64:67]
	v_mfma_f32_16x16x32_bf16 v[116:119], v[156:159], v[188:191], v[116:119]
	v_mfma_f32_16x16x32_bf16 v[108:111], v[164:167], v[188:191], v[108:111]
	v_mfma_f32_16x16x32_bf16 v[100:103], v[156:159], v[208:211], v[100:103]
	v_mfma_f32_16x16x32_bf16 v[92:95], v[164:167], v[208:211], v[92:95]
	v_mfma_f32_16x16x32_bf16 v[84:87], v[156:159], v[216:219], v[84:87]
	v_mfma_f32_16x16x32_bf16 v[76:79], v[164:167], v[216:219], v[76:79]
	v_mfma_f32_16x16x32_bf16 v[68:71], v[156:159], v[224:227], v[68:71]
	v_mfma_f32_16x16x32_bf16 v[64:67], v[164:167], v[224:227], v[64:67]
	s_setprio 0
	s_barrier
	s_add_i32 s26, s62, s31
	v_lshl_add_u64 v[174:175], v[174:175], 0, s[94:95]
	s_mov_b32 m0, s26
	ds_read_b128 v[168:171], v135 offset:49152
	ds_read_b128 v[188:191], v135 offset:50176
	ds_read_b128 v[204:207], v135 offset:51200
	ds_read_b128 v[208:211], v135 offset:52224
	ds_read_b128 v[212:215], v135 offset:53248
	ds_read_b128 v[216:219], v135 offset:54272
	ds_read_b128 v[220:223], v135 offset:55296
	ds_read_b128 v[224:227], v135 offset:56320
	global_load_lds_dwordx4 v[174:175], off
	s_add_i32 m0, s26, 0x2000
	s_add_u32 s24, s24, 0x40080
	v_lshl_add_u64 v[174:175], v[176:177], 0, s[94:95]
	s_addc_u32 s25, s25, 0
	s_add_i32 s26, s63, s31
	global_load_lds_dwordx4 v[174:175], off
	v_lshl_add_u64 v[174:175], s[24:25], 0, v[128:129]
	s_mov_b32 m0, s26
	s_nop 0
	global_load_lds_dwordx4 v[174:175], off
	v_lshl_add_u64 v[174:175], s[24:25], 0, v[132:133]
	s_add_i32 m0, s26, 0x2000
	s_nop 0
	global_load_lds_dwordx4 v[174:175], off
	v_lshl_add_u64 v[174:175], v[180:181], 0, s[94:95]
	s_mov_b32 m0, s54
	s_nop 0
	global_load_lds_dwordx4 v[174:175], off
	v_lshl_add_u64 v[174:175], v[182:183], 0, s[94:95]
	s_mov_b32 m0, s55
	s_nop 0
	global_load_lds_dwordx4 v[174:175], off
	s_waitcnt vmcnt(8)
	s_waitcnt lgkmcnt(0)
	s_barrier
	s_setprio 1
	s_waitcnt lgkmcnt(0)
	v_mfma_f32_16x16x32_bf16 v[60:63], v[136:139], v[168:171], v[60:63]
	v_mfma_f32_16x16x32_bf16 v[56:59], v[144:147], v[168:171], v[56:59]
	v_mfma_f32_16x16x32_bf16 v[48:51], v[136:139], v[204:207], v[48:51]
	v_mfma_f32_16x16x32_bf16 v[40:43], v[144:147], v[204:207], v[40:43]
	v_mfma_f32_16x16x32_bf16 v[32:35], v[136:139], v[212:215], v[32:35]
	v_mfma_f32_16x16x32_bf16 v[24:27], v[144:147], v[212:215], v[24:27]
	v_mfma_f32_16x16x32_bf16 v[16:19], v[136:139], v[220:223], v[16:19]
	v_mfma_f32_16x16x32_bf16 v[8:11], v[144:147], v[220:223], v[8:11]
	v_mfma_f32_16x16x32_bf16 v[60:63], v[140:143], v[188:191], v[60:63]
	v_mfma_f32_16x16x32_bf16 v[56:59], v[148:151], v[188:191], v[56:59]
	v_mfma_f32_16x16x32_bf16 v[48:51], v[140:143], v[208:211], v[48:51]
	v_mfma_f32_16x16x32_bf16 v[40:43], v[148:151], v[208:211], v[40:43]
	v_mfma_f32_16x16x32_bf16 v[32:35], v[140:143], v[216:219], v[32:35]
	v_mfma_f32_16x16x32_bf16 v[24:27], v[148:151], v[216:219], v[24:27]
	v_mfma_f32_16x16x32_bf16 v[16:19], v[140:143], v[224:227], v[16:19]
	v_mfma_f32_16x16x32_bf16 v[8:11], v[148:151], v[224:227], v[8:11]
	s_setprio 0
	s_setprio 1
	v_mfma_f32_16x16x32_bf16 v[52:55], v[152:155], v[168:171], v[52:55]
	v_mfma_f32_16x16x32_bf16 v[44:47], v[160:163], v[168:171], v[44:47]
	v_mfma_f32_16x16x32_bf16 v[36:39], v[152:155], v[204:207], v[36:39]
	v_mfma_f32_16x16x32_bf16 v[28:31], v[160:163], v[204:207], v[28:31]
	v_mfma_f32_16x16x32_bf16 v[20:23], v[152:155], v[212:215], v[20:23]
	v_mfma_f32_16x16x32_bf16 v[12:15], v[160:163], v[212:215], v[12:15]
	v_mfma_f32_16x16x32_bf16 v[4:7], v[152:155], v[220:223], v[4:7]
	v_mfma_f32_16x16x32_bf16 v[0:3], v[160:163], v[220:223], v[0:3]
	v_mfma_f32_16x16x32_bf16 v[52:55], v[156:159], v[188:191], v[52:55]
	v_mfma_f32_16x16x32_bf16 v[44:47], v[164:167], v[188:191], v[44:47]
	v_mfma_f32_16x16x32_bf16 v[36:39], v[156:159], v[208:211], v[36:39]
	v_mfma_f32_16x16x32_bf16 v[28:31], v[164:167], v[208:211], v[28:31]
	v_mfma_f32_16x16x32_bf16 v[20:23], v[156:159], v[216:219], v[20:23]
	v_mfma_f32_16x16x32_bf16 v[12:15], v[164:167], v[216:219], v[12:15]
	v_mfma_f32_16x16x32_bf16 v[4:7], v[156:159], v[224:227], v[4:7]
	v_mfma_f32_16x16x32_bf16 v[0:3], v[164:167], v[224:227], v[0:3]
	s_setprio 0
	s_add_i32 s61, s61, 2
	s_add_u32 s22, s22, 0x100
	s_addc_u32 s23, s23, 0
	s_add_u32 s15, s15, 0x100
	s_addc_u32 s17, s17, 0
	s_cmp_gt_u32 s61, 13
	s_cbranch_scc1 .Lkrot3_exit
	s_add_u32 s24, s22, 0xfffc0080
	s_addc_u32 s25, s23, -1
	s_add_i32 s62, 0, 0x10000
	s_cmp_eq_u32 s61, 12
	s_cselect_b32 s27, s19, s25
	s_cselect_b32 s26, s18, s24
	s_cselect_b32 s25, s21, s17
	s_cselect_b32 s24, s20, s15
	s_add_i32 s64, 0, 0x14000
	s_barrier
	s_branch .LBB0_747

.LBB0_876:
	s_add_i32 s19, s64, -2
	s_add_u32 s6, s24, 0x40080
	s_addc_u32 s7, s25, 0
	v_add_u32_e32 v1, s54, v1
	v_add_u32_e32 v134, s56, v0
	s_add_u32 s26, s22, 0x100
	v_mov_b32_e32 v0, 0
	v_mov_b32_e32 v131, v173
	v_mov_b32_e32 v129, v173
	v_mov_b32_e32 v133, v173
	s_addc_u32 s27, s23, 0
	s_mov_b32 s22, 0
	v_add_u32_e32 v135, 0, v1
	v_mov_b32_e32 v1, v0
	v_mov_b32_e32 v2, v0
	v_mov_b32_e32 v3, v0
	v_mov_b32_e32 v4, v0
	v_mov_b32_e32 v5, v0
	v_mov_b32_e32 v6, v0
	v_mov_b32_e32 v7, v0
	v_mov_b32_e32 v8, v0
	v_mov_b32_e32 v9, v0
	v_mov_b32_e32 v10, v0
	v_mov_b32_e32 v11, v0
	v_mov_b32_e32 v16, v0
	v_mov_b32_e32 v17, v0
	v_mov_b32_e32 v18, v0
	v_mov_b32_e32 v19, v0
	v_mov_b32_e32 v24, v0
	v_mov_b32_e32 v25, v0
	v_mov_b32_e32 v26, v0
	v_mov_b32_e32 v27, v0
	v_mov_b32_e32 v32, v0
	v_mov_b32_e32 v33, v0
	v_mov_b32_e32 v34, v0
	v_mov_b32_e32 v35, v0
	v_mov_b32_e32 v40, v0
	v_mov_b32_e32 v41, v0
	v_mov_b32_e32 v42, v0
	v_mov_b32_e32 v43, v0
	v_mov_b32_e32 v48, v0
	v_mov_b32_e32 v49, v0
	v_mov_b32_e32 v50, v0
	v_mov_b32_e32 v51, v0
	v_mov_b32_e32 v12, v0
	v_mov_b32_e32 v13, v0
	v_mov_b32_e32 v14, v0
	v_mov_b32_e32 v15, v0
	v_mov_b32_e32 v20, v0
	v_mov_b32_e32 v21, v0
	v_mov_b32_e32 v22, v0
	v_mov_b32_e32 v23, v0
	v_mov_b32_e32 v28, v0
	v_mov_b32_e32 v29, v0
	v_mov_b32_e32 v30, v0
	v_mov_b32_e32 v31, v0
	v_mov_b32_e32 v36, v0
	v_mov_b32_e32 v37, v0
	v_mov_b32_e32 v38, v0
	v_mov_b32_e32 v39, v0
	v_mov_b32_e32 v44, v0
	v_mov_b32_e32 v45, v0
	v_mov_b32_e32 v46, v0
	v_mov_b32_e32 v47, v0
	v_mov_b32_e32 v52, v0
	v_mov_b32_e32 v53, v0
	v_mov_b32_e32 v54, v0
	v_mov_b32_e32 v55, v0
	v_mov_b32_e32 v56, v0
	v_mov_b32_e32 v57, v0
	v_mov_b32_e32 v58, v0
	v_mov_b32_e32 v59, v0
	v_mov_b32_e32 v60, v0
	v_mov_b32_e32 v61, v0
	v_mov_b32_e32 v62, v0
	v_mov_b32_e32 v63, v0
	v_mov_b32_e32 v64, v0
	v_mov_b32_e32 v65, v0
	v_mov_b32_e32 v66, v0
	v_mov_b32_e32 v67, v0
	v_mov_b32_e32 v68, v0
	v_mov_b32_e32 v69, v0
	v_mov_b32_e32 v70, v0
	v_mov_b32_e32 v71, v0
	v_mov_b32_e32 v72, v0
	v_mov_b32_e32 v73, v0
	v_mov_b32_e32 v74, v0
	v_mov_b32_e32 v75, v0
	v_mov_b32_e32 v80, v0
	v_mov_b32_e32 v81, v0
	v_mov_b32_e32 v82, v0
	v_mov_b32_e32 v83, v0
	v_mov_b32_e32 v88, v0
	v_mov_b32_e32 v89, v0
	v_mov_b32_e32 v90, v0
	v_mov_b32_e32 v91, v0
	v_mov_b32_e32 v96, v0
	v_mov_b32_e32 v97, v0
	v_mov_b32_e32 v98, v0
	v_mov_b32_e32 v99, v0
	v_mov_b32_e32 v104, v0
	v_mov_b32_e32 v105, v0
	v_mov_b32_e32 v106, v0
	v_mov_b32_e32 v107, v0
	v_mov_b32_e32 v112, v0
	v_mov_b32_e32 v113, v0
	v_mov_b32_e32 v114, v0
	v_mov_b32_e32 v115, v0
	v_mov_b32_e32 v76, v0
	v_mov_b32_e32 v77, v0
	v_mov_b32_e32 v78, v0
	v_mov_b32_e32 v79, v0
	v_mov_b32_e32 v84, v0
	v_mov_b32_e32 v85, v0
	v_mov_b32_e32 v86, v0
	v_mov_b32_e32 v87, v0
	v_mov_b32_e32 v92, v0
	v_mov_b32_e32 v93, v0
	v_mov_b32_e32 v94, v0
	v_mov_b32_e32 v95, v0
	v_mov_b32_e32 v100, v0
	v_mov_b32_e32 v101, v0
	v_mov_b32_e32 v102, v0
	v_mov_b32_e32 v103, v0
	v_mov_b32_e32 v108, v0
	v_mov_b32_e32 v109, v0
	v_mov_b32_e32 v110, v0
	v_mov_b32_e32 v111, v0
	v_mov_b32_e32 v116, v0
	v_mov_b32_e32 v117, v0
	v_mov_b32_e32 v118, v0
	v_mov_b32_e32 v119, v0
	v_mov_b32_e32 v120, v0
	v_mov_b32_e32 v121, v0
	v_mov_b32_e32 v122, v0
	v_mov_b32_e32 v123, v0
	v_mov_b32_e32 v124, v0
	v_mov_b32_e32 v125, v0
	v_mov_b32_e32 v126, v0
	v_mov_b32_e32 v127, v0
	s_add_i32 s67, s22, 2
	s_add_u32 s23, s6, 0xfffc0080
	s_addc_u32 s24, s7, -1
	s_add_i32 s68, 0, 0x10000
	s_cmp_eq_u32 s19, s22
	s_cselect_b32 s25, s9, s24
	s_cselect_b32 s24, s8, s23
	s_cselect_b32 s23, s21, s27
	s_cselect_b32 s22, s20, s26
	s_add_i32 s70, 0, 0x14000
.LBB0_877:
	v_add_u32_e32 v148, s68, v134
	v_add_u32_e32 v164, s70, v134
	ds_read_b128 v[136:139], v148
	ds_read_b128 v[140:143], v148 offset:1024
	ds_read_b128 v[144:147], v148 offset:2048
	ds_read_b128 v[148:151], v148 offset:3072
	ds_read_b128 v[152:155], v164
	ds_read_b128 v[156:159], v164 offset:1024
	ds_read_b128 v[160:163], v164 offset:2048
	ds_read_b128 v[164:167], v164 offset:3072
	v_lshl_add_u64 v[174:175], s[6:7], 0, v[172:173]
	s_add_i32 m0, s37, 0xc000
	ds_read_b128 v[168:171], v135
	ds_read_b128 v[188:191], v135 offset:1024
	ds_read_b128 v[204:207], v135 offset:2048
	ds_read_b128 v[208:211], v135 offset:3072
	ds_read_b128 v[212:215], v135 offset:4096
	ds_read_b128 v[216:219], v135 offset:5120
	ds_read_b128 v[220:223], v135 offset:6144
	ds_read_b128 v[224:227], v135 offset:7168
	global_load_lds_dwordx4 v[174:175], off
	v_lshl_add_u64 v[174:175], s[6:7], 0, v[130:131]
	s_add_i32 m0, s37, 0xe000
	s_nop 0
	global_load_lds_dwordx4 v[174:175], off
	s_waitcnt vmcnt(8)
	s_waitcnt lgkmcnt(0)
	s_barrier
	s_setprio 1
	s_waitcnt lgkmcnt(0)
	v_mfma_f32_16x16x32_bf16 v[124:127], v[136:139], v[168:171], v[124:127]
	v_mfma_f32_16x16x32_bf16 v[120:123], v[144:147], v[168:171], v[120:123]
	v_mfma_f32_16x16x32_bf16 v[116:119], v[136:139], v[204:207], v[116:119]
	v_mfma_f32_16x16x32_bf16 v[108:111], v[144:147], v[204:207], v[108:111]
	v_mfma_f32_16x16x32_bf16 v[100:103], v[136:139], v[212:215], v[100:103]
	v_mfma_f32_16x16x32_bf16 v[92:95], v[144:147], v[212:215], v[92:95]
	v_mfma_f32_16x16x32_bf16 v[84:87], v[136:139], v[220:223], v[84:87]
	v_mfma_f32_16x16x32_bf16 v[76:79], v[144:147], v[220:223], v[76:79]
	v_mfma_f32_16x16x32_bf16 v[124:127], v[140:143], v[188:191], v[124:127]
	v_mfma_f32_16x16x32_bf16 v[120:123], v[148:151], v[188:191], v[120:123]
	v_mfma_f32_16x16x32_bf16 v[116:119], v[140:143], v[208:211], v[116:119]
	v_mfma_f32_16x16x32_bf16 v[108:111], v[148:151], v[208:211], v[108:111]
	v_mfma_f32_16x16x32_bf16 v[100:103], v[140:143], v[216:219], v[100:103]
	v_mfma_f32_16x16x32_bf16 v[92:95], v[148:151], v[216:219], v[92:95]
	v_mfma_f32_16x16x32_bf16 v[84:87], v[140:143], v[224:227], v[84:87]
	v_mfma_f32_16x16x32_bf16 v[76:79], v[148:151], v[224:227], v[76:79]
	s_setprio 0
	s_setprio 1
	v_mfma_f32_16x16x32_bf16 v[112:115], v[152:155], v[168:171], v[112:115]
	v_mfma_f32_16x16x32_bf16 v[104:107], v[160:163], v[168:171], v[104:107]
	v_mfma_f32_16x16x32_bf16 v[96:99], v[152:155], v[204:207], v[96:99]
	v_mfma_f32_16x16x32_bf16 v[88:91], v[160:163], v[204:207], v[88:91]
	v_mfma_f32_16x16x32_bf16 v[80:83], v[152:155], v[212:215], v[80:83]
	v_mfma_f32_16x16x32_bf16 v[72:75], v[160:163], v[212:215], v[72:75]
	v_mfma_f32_16x16x32_bf16 v[68:71], v[152:155], v[220:223], v[68:71]
	v_mfma_f32_16x16x32_bf16 v[64:67], v[160:163], v[220:223], v[64:67]
	v_mfma_f32_16x16x32_bf16 v[112:115], v[156:159], v[188:191], v[112:115]
	v_mfma_f32_16x16x32_bf16 v[104:107], v[164:167], v[188:191], v[104:107]
	v_mfma_f32_16x16x32_bf16 v[96:99], v[156:159], v[208:211], v[96:99]
	v_mfma_f32_16x16x32_bf16 v[88:91], v[164:167], v[208:211], v[88:91]
	v_mfma_f32_16x16x32_bf16 v[80:83], v[156:159], v[216:219], v[80:83]
	v_mfma_f32_16x16x32_bf16 v[72:75], v[164:167], v[216:219], v[72:75]
	v_mfma_f32_16x16x32_bf16 v[68:71], v[156:159], v[224:227], v[68:71]
	v_mfma_f32_16x16x32_bf16 v[64:67], v[164:167], v[224:227], v[64:67]
	s_setprio 0
	s_barrier
	s_add_i32 s68, s68, s36
	v_lshl_add_u64 v[174:175], s[22:23], 0, v[128:129]
	s_mov_b32 m0, s68
	ds_read_b128 v[168:171], v135 offset:16384
	ds_read_b128 v[188:191], v135 offset:17408
	ds_read_b128 v[204:207], v135 offset:18432
	ds_read_b128 v[208:211], v135 offset:19456
	ds_read_b128 v[212:215], v135 offset:20480
	ds_read_b128 v[216:219], v135 offset:21504
	ds_read_b128 v[220:223], v135 offset:22528
	ds_read_b128 v[224:227], v135 offset:23552
	global_load_lds_dwordx4 v[174:175], off
	s_add_i32 m0, s68, 0x2000
	s_add_u32 s68, s22, 0x40000
	v_lshl_add_u64 v[176:177], s[22:23], 0, v[132:133]
	s_addc_u32 s69, s23, 0
	s_add_i32 s70, s70, s36
	global_load_lds_dwordx4 v[176:177], off
	v_lshl_add_u64 v[180:181], s[68:69], 0, v[128:129]
	s_mov_b32 m0, s70
	v_lshl_add_u64 v[182:183], s[24:25], 0, v[130:131]
	global_load_lds_dwordx4 v[180:181], off
	v_lshl_add_u64 v[180:181], s[68:69], 0, v[132:133]
	s_add_i32 m0, s70, 0x2000
	s_nop 0
	global_load_lds_dwordx4 v[180:181], off
	v_lshl_add_u64 v[180:181], s[24:25], 0, v[172:173]
	s_mov_b32 m0, s37
	s_nop 0
	global_load_lds_dwordx4 v[180:181], off
	s_mov_b32 m0, s38
	s_nop 0
	global_load_lds_dwordx4 v[182:183], off
	s_waitcnt vmcnt(8)
	s_waitcnt lgkmcnt(0)
	s_barrier
	s_setprio 1
	s_waitcnt lgkmcnt(0)
	v_mfma_f32_16x16x32_bf16 v[60:63], v[136:139], v[168:171], v[60:63]
	v_mfma_f32_16x16x32_bf16 v[56:59], v[144:147], v[168:171], v[56:59]
	v_mfma_f32_16x16x32_bf16 v[52:55], v[136:139], v[204:207], v[52:55]
	v_mfma_f32_16x16x32_bf16 v[44:47], v[144:147], v[204:207], v[44:47]
	v_mfma_f32_16x16x32_bf16 v[36:39], v[136:139], v[212:215], v[36:39]
	v_mfma_f32_16x16x32_bf16 v[28:31], v[144:147], v[212:215], v[28:31]
	v_mfma_f32_16x16x32_bf16 v[20:23], v[136:139], v[220:223], v[20:23]
	v_mfma_f32_16x16x32_bf16 v[12:15], v[144:147], v[220:223], v[12:15]
	v_mfma_f32_16x16x32_bf16 v[60:63], v[140:143], v[188:191], v[60:63]
	v_mfma_f32_16x16x32_bf16 v[56:59], v[148:151], v[188:191], v[56:59]
	v_mfma_f32_16x16x32_bf16 v[52:55], v[140:143], v[208:211], v[52:55]
	v_mfma_f32_16x16x32_bf16 v[44:47], v[148:151], v[208:211], v[44:47]
	v_mfma_f32_16x16x32_bf16 v[36:39], v[140:143], v[216:219], v[36:39]
	v_mfma_f32_16x16x32_bf16 v[28:31], v[148:151], v[216:219], v[28:31]
	v_mfma_f32_16x16x32_bf16 v[20:23], v[140:143], v[224:227], v[20:23]
	v_mfma_f32_16x16x32_bf16 v[12:15], v[148:151], v[224:227], v[12:15]
	s_setprio 0
	s_setprio 1
	v_mfma_f32_16x16x32_bf16 v[48:51], v[152:155], v[168:171], v[48:51]
	v_mfma_f32_16x16x32_bf16 v[40:43], v[160:163], v[168:171], v[40:43]
	v_mfma_f32_16x16x32_bf16 v[32:35], v[152:155], v[204:207], v[32:35]
	v_mfma_f32_16x16x32_bf16 v[24:27], v[160:163], v[204:207], v[24:27]
	v_mfma_f32_16x16x32_bf16 v[16:19], v[152:155], v[212:215], v[16:19]
	v_mfma_f32_16x16x32_bf16 v[8:11], v[160:163], v[212:215], v[8:11]
	v_mfma_f32_16x16x32_bf16 v[4:7], v[152:155], v[220:223], v[4:7]
	v_mfma_f32_16x16x32_bf16 v[0:3], v[160:163], v[220:223], v[0:3]
	v_mfma_f32_16x16x32_bf16 v[48:51], v[156:159], v[188:191], v[48:51]
	v_mfma_f32_16x16x32_bf16 v[40:43], v[164:167], v[188:191], v[40:43]
	v_mfma_f32_16x16x32_bf16 v[32:35], v[156:159], v[208:211], v[32:35]
	v_mfma_f32_16x16x32_bf16 v[24:27], v[164:167], v[208:211], v[24:27]
	v_mfma_f32_16x16x32_bf16 v[16:19], v[156:159], v[216:219], v[16:19]
	v_mfma_f32_16x16x32_bf16 v[8:11], v[164:167], v[216:219], v[8:11]
	v_mfma_f32_16x16x32_bf16 v[4:7], v[156:159], v[224:227], v[4:7]
	v_mfma_f32_16x16x32_bf16 v[0:3], v[164:167], v[224:227], v[0:3]
	s_setprio 0
	s_barrier
	s_add_i32 s68, 0, 0x18000
	s_add_i32 s69, 0, 0x1c000
	v_add_u32_e32 v148, s68, v134
	v_add_u32_e32 v164, s69, v134
	ds_read_b128 v[136:139], v148
	ds_read_b128 v[140:143], v148 offset:1024
	ds_read_b128 v[144:147], v148 offset:2048
	ds_read_b128 v[148:151], v148 offset:3072
	ds_read_b128 v[152:155], v164
	ds_read_b128 v[156:159], v164 offset:1024
	ds_read_b128 v[160:163], v164 offset:2048
	ds_read_b128 v[164:167], v164 offset:3072
	s_add_u32 s24, s24, 0x40000
	s_addc_u32 s25, s25, 0
	s_mov_b32 m0, s39
	v_lshl_add_u64 v[228:229], s[24:25], 0, v[172:173]
	ds_read_b128 v[168:171], v135 offset:32768
	ds_read_b128 v[188:191], v135 offset:33792
	ds_read_b128 v[204:207], v135 offset:34816
	ds_read_b128 v[208:211], v135 offset:35840
	ds_read_b128 v[212:215], v135 offset:36864
	ds_read_b128 v[216:219], v135 offset:37888
	ds_read_b128 v[220:223], v135 offset:38912
	ds_read_b128 v[224:227], v135 offset:39936
	global_load_lds_dwordx4 v[228:229], off
	v_lshl_add_u64 v[228:229], s[24:25], 0, v[130:131]
	s_mov_b32 m0, s44
	s_nop 0
	global_load_lds_dwordx4 v[228:229], off
	s_waitcnt vmcnt(8)
	s_waitcnt lgkmcnt(0)
	s_barrier
	s_setprio 1
	s_waitcnt lgkmcnt(0)
	v_mfma_f32_16x16x32_bf16 v[124:127], v[136:139], v[168:171], v[124:127]
	v_mfma_f32_16x16x32_bf16 v[120:123], v[144:147], v[168:171], v[120:123]
	v_mfma_f32_16x16x32_bf16 v[116:119], v[136:139], v[204:207], v[116:119]
	v_mfma_f32_16x16x32_bf16 v[108:111], v[144:147], v[204:207], v[108:111]
	v_mfma_f32_16x16x32_bf16 v[100:103], v[136:139], v[212:215], v[100:103]
	v_mfma_f32_16x16x32_bf16 v[92:95], v[144:147], v[212:215], v[92:95]
	v_mfma_f32_16x16x32_bf16 v[84:87], v[136:139], v[220:223], v[84:87]
	v_mfma_f32_16x16x32_bf16 v[76:79], v[144:147], v[220:223], v[76:79]
	v_mfma_f32_16x16x32_bf16 v[124:127], v[140:143], v[188:191], v[124:127]
	v_mfma_f32_16x16x32_bf16 v[120:123], v[148:151], v[188:191], v[120:123]
	v_mfma_f32_16x16x32_bf16 v[116:119], v[140:143], v[208:211], v[116:119]
	v_mfma_f32_16x16x32_bf16 v[108:111], v[148:151], v[208:211], v[108:111]
	v_mfma_f32_16x16x32_bf16 v[100:103], v[140:143], v[216:219], v[100:103]
	v_mfma_f32_16x16x32_bf16 v[92:95], v[148:151], v[216:219], v[92:95]
	v_mfma_f32_16x16x32_bf16 v[84:87], v[140:143], v[224:227], v[84:87]
	v_mfma_f32_16x16x32_bf16 v[76:79], v[148:151], v[224:227], v[76:79]
	s_setprio 0
	s_setprio 1
	v_mfma_f32_16x16x32_bf16 v[112:115], v[152:155], v[168:171], v[112:115]
	v_mfma_f32_16x16x32_bf16 v[104:107], v[160:163], v[168:171], v[104:107]
	v_mfma_f32_16x16x32_bf16 v[96:99], v[152:155], v[204:207], v[96:99]
	v_mfma_f32_16x16x32_bf16 v[88:91], v[160:163], v[204:207], v[88:91]
	v_mfma_f32_16x16x32_bf16 v[80:83], v[152:155], v[212:215], v[80:83]
	v_mfma_f32_16x16x32_bf16 v[72:75], v[160:163], v[212:215], v[72:75]
	v_mfma_f32_16x16x32_bf16 v[68:71], v[152:155], v[220:223], v[68:71]
	v_mfma_f32_16x16x32_bf16 v[64:67], v[160:163], v[220:223], v[64:67]
	v_mfma_f32_16x16x32_bf16 v[112:115], v[156:159], v[188:191], v[112:115]
	v_mfma_f32_16x16x32_bf16 v[104:107], v[164:167], v[188:191], v[104:107]
	v_mfma_f32_16x16x32_bf16 v[96:99], v[156:159], v[208:211], v[96:99]
	v_mfma_f32_16x16x32_bf16 v[88:91], v[164:167], v[208:211], v[88:91]
	v_mfma_f32_16x16x32_bf16 v[80:83], v[156:159], v[216:219], v[80:83]
	v_mfma_f32_16x16x32_bf16 v[72:75], v[164:167], v[216:219], v[72:75]
	v_mfma_f32_16x16x32_bf16 v[68:71], v[156:159], v[224:227], v[68:71]
	v_mfma_f32_16x16x32_bf16 v[64:67], v[164:167], v[224:227], v[64:67]
	s_setprio 0
	s_barrier
	s_add_i32 s24, s68, s36
	v_lshl_add_u64 v[174:175], v[174:175], 0, s[94:95]
	s_mov_b32 m0, s24
	ds_read_b128 v[168:171], v135 offset:49152
	ds_read_b128 v[188:191], v135 offset:50176
	ds_read_b128 v[204:207], v135 offset:51200
	ds_read_b128 v[208:211], v135 offset:52224
	ds_read_b128 v[212:215], v135 offset:53248
	ds_read_b128 v[216:219], v135 offset:54272
	ds_read_b128 v[220:223], v135 offset:55296
	ds_read_b128 v[224:227], v135 offset:56320
	global_load_lds_dwordx4 v[174:175], off
	s_add_i32 m0, s24, 0x2000
	s_add_u32 s22, s22, 0x40080
	v_lshl_add_u64 v[174:175], v[176:177], 0, s[94:95]
	s_addc_u32 s23, s23, 0
	s_add_i32 s24, s69, s36
	global_load_lds_dwordx4 v[174:175], off
	v_lshl_add_u64 v[174:175], s[22:23], 0, v[128:129]
	s_mov_b32 m0, s24
	s_nop 0
	global_load_lds_dwordx4 v[174:175], off
	v_lshl_add_u64 v[174:175], s[22:23], 0, v[132:133]
	s_add_i32 m0, s24, 0x2000
	s_nop 0
	global_load_lds_dwordx4 v[174:175], off
	v_lshl_add_u64 v[174:175], v[180:181], 0, s[94:95]
	s_mov_b32 m0, s57
	s_nop 0
	global_load_lds_dwordx4 v[174:175], off
	v_lshl_add_u64 v[174:175], v[182:183], 0, s[94:95]
	s_mov_b32 m0, s60
	s_nop 0
	global_load_lds_dwordx4 v[174:175], off
	s_waitcnt vmcnt(8)
	s_waitcnt lgkmcnt(0)
	s_barrier
	s_setprio 1
	s_waitcnt lgkmcnt(0)
	v_mfma_f32_16x16x32_bf16 v[60:63], v[136:139], v[168:171], v[60:63]
	v_mfma_f32_16x16x32_bf16 v[56:59], v[144:147], v[168:171], v[56:59]
	v_mfma_f32_16x16x32_bf16 v[52:55], v[136:139], v[204:207], v[52:55]
	v_mfma_f32_16x16x32_bf16 v[44:47], v[144:147], v[204:207], v[44:47]
	v_mfma_f32_16x16x32_bf16 v[36:39], v[136:139], v[212:215], v[36:39]
	v_mfma_f32_16x16x32_bf16 v[28:31], v[144:147], v[212:215], v[28:31]
	v_mfma_f32_16x16x32_bf16 v[20:23], v[136:139], v[220:223], v[20:23]
	v_mfma_f32_16x16x32_bf16 v[12:15], v[144:147], v[220:223], v[12:15]
	v_mfma_f32_16x16x32_bf16 v[60:63], v[140:143], v[188:191], v[60:63]
	v_mfma_f32_16x16x32_bf16 v[56:59], v[148:151], v[188:191], v[56:59]
	v_mfma_f32_16x16x32_bf16 v[52:55], v[140:143], v[208:211], v[52:55]
	v_mfma_f32_16x16x32_bf16 v[44:47], v[148:151], v[208:211], v[44:47]
	v_mfma_f32_16x16x32_bf16 v[36:39], v[140:143], v[216:219], v[36:39]
	v_mfma_f32_16x16x32_bf16 v[28:31], v[148:151], v[216:219], v[28:31]
	v_mfma_f32_16x16x32_bf16 v[20:23], v[140:143], v[224:227], v[20:23]
	v_mfma_f32_16x16x32_bf16 v[12:15], v[148:151], v[224:227], v[12:15]
	s_setprio 0
	s_setprio 1
	v_mfma_f32_16x16x32_bf16 v[48:51], v[152:155], v[168:171], v[48:51]
	v_mfma_f32_16x16x32_bf16 v[40:43], v[160:163], v[168:171], v[40:43]
	v_mfma_f32_16x16x32_bf16 v[32:35], v[152:155], v[204:207], v[32:35]
	v_mfma_f32_16x16x32_bf16 v[24:27], v[160:163], v[204:207], v[24:27]
	v_mfma_f32_16x16x32_bf16 v[16:19], v[152:155], v[212:215], v[16:19]
	v_mfma_f32_16x16x32_bf16 v[8:11], v[160:163], v[212:215], v[8:11]
	v_mfma_f32_16x16x32_bf16 v[4:7], v[152:155], v[220:223], v[4:7]
	v_mfma_f32_16x16x32_bf16 v[0:3], v[160:163], v[220:223], v[0:3]
	v_mfma_f32_16x16x32_bf16 v[48:51], v[156:159], v[188:191], v[48:51]
	v_mfma_f32_16x16x32_bf16 v[40:43], v[164:167], v[188:191], v[40:43]
	v_mfma_f32_16x16x32_bf16 v[32:35], v[156:159], v[208:211], v[32:35]
	v_mfma_f32_16x16x32_bf16 v[24:27], v[164:167], v[208:211], v[24:27]
	v_mfma_f32_16x16x32_bf16 v[16:19], v[156:159], v[216:219], v[16:19]
	v_mfma_f32_16x16x32_bf16 v[8:11], v[164:167], v[216:219], v[8:11]
	v_mfma_f32_16x16x32_bf16 v[4:7], v[156:159], v[224:227], v[4:7]
	v_mfma_f32_16x16x32_bf16 v[0:3], v[164:167], v[224:227], v[0:3]
	s_setprio 0
	s_add_u32 s6, s6, 0x100
	s_addc_u32 s7, s7, 0
	s_add_u32 s26, s26, 0x100
	s_addc_u32 s27, s27, 0
	s_cmp_ge_i32 s67, s64
	s_mov_b32 s22, s67
	s_cbranch_scc1 .Lkrot4_exit
	s_add_i32 s67, s22, 2
	s_add_u32 s23, s6, 0xfffc0080
	s_addc_u32 s24, s7, -1
	s_add_i32 s68, 0, 0x10000
	s_cmp_eq_u32 s19, s22
	s_cselect_b32 s25, s9, s24
	s_cselect_b32 s24, s8, s23
	s_cselect_b32 s23, s21, s27
	s_cselect_b32 s22, s20, s26
	s_add_i32 s70, 0, 0x14000
	s_barrier
	s_branch .LBB0_877
.Lkrot4_exit:
	s_barrier
	s_and_b64 vcc, exec, s[14:15]
	s_cbranch_vccz .LBB0_880
	s_barrier

.LBB0_989:
	s_add_u32 s6, s10, 0x20080
	s_addc_u32 s7, s11, 0
	v_add_u32_e32 v1, s57, v1
	v_add_u32_e32 v134, s63, v0
	s_add_u32 s25, s8, 0x100
	v_mov_b32_e32 v0, 0
	v_mov_b32_e32 v133, v173
	v_mov_b32_e32 v129, v173
	v_mov_b32_e32 v131, v173
	s_addc_u32 s31, s9, 0
	s_mov_b32 s69, -2
	v_add_u32_e32 v135, 0, v1
	v_mov_b32_e32 v1, v0
	v_mov_b32_e32 v2, v0
	v_mov_b32_e32 v3, v0
	v_mov_b32_e32 v8, v0
	v_mov_b32_e32 v9, v0
	v_mov_b32_e32 v10, v0
	v_mov_b32_e32 v11, v0
	v_mov_b32_e32 v16, v0
	v_mov_b32_e32 v17, v0
	v_mov_b32_e32 v18, v0
	v_mov_b32_e32 v19, v0
	v_mov_b32_e32 v20, v0
	v_mov_b32_e32 v21, v0
	v_mov_b32_e32 v22, v0
	v_mov_b32_e32 v23, v0
	v_mov_b32_e32 v32, v0
	v_mov_b32_e32 v33, v0
	v_mov_b32_e32 v34, v0
	v_mov_b32_e32 v35, v0
	v_mov_b32_e32 v36, v0
	v_mov_b32_e32 v37, v0
	v_mov_b32_e32 v38, v0
	v_mov_b32_e32 v39, v0
	v_mov_b32_e32 v48, v0
	v_mov_b32_e32 v49, v0
	v_mov_b32_e32 v50, v0
	v_mov_b32_e32 v51, v0
	v_mov_b32_e32 v52, v0
	v_mov_b32_e32 v53, v0
	v_mov_b32_e32 v54, v0
	v_mov_b32_e32 v55, v0
	v_mov_b32_e32 v12, v0
	v_mov_b32_e32 v13, v0
	v_mov_b32_e32 v14, v0
	v_mov_b32_e32 v15, v0
	v_mov_b32_e32 v4, v0
	v_mov_b32_e32 v5, v0
	v_mov_b32_e32 v6, v0
	v_mov_b32_e32 v7, v0
	v_mov_b32_e32 v24, v0
	v_mov_b32_e32 v25, v0
	v_mov_b32_e32 v26, v0
	v_mov_b32_e32 v27, v0
	v_mov_b32_e32 v28, v0
	v_mov_b32_e32 v29, v0
	v_mov_b32_e32 v30, v0
	v_mov_b32_e32 v31, v0
	v_mov_b32_e32 v40, v0
	v_mov_b32_e32 v41, v0
	v_mov_b32_e32 v42, v0
	v_mov_b32_e32 v43, v0
	v_mov_b32_e32 v44, v0
	v_mov_b32_e32 v45, v0
	v_mov_b32_e32 v46, v0
	v_mov_b32_e32 v47, v0
	v_mov_b32_e32 v56, v0
	v_mov_b32_e32 v57, v0
	v_mov_b32_e32 v58, v0
	v_mov_b32_e32 v59, v0
	v_mov_b32_e32 v60, v0
	v_mov_b32_e32 v61, v0
	v_mov_b32_e32 v62, v0
	v_mov_b32_e32 v63, v0
	v_mov_b32_e32 v64, v0
	v_mov_b32_e32 v65, v0
	v_mov_b32_e32 v66, v0
	v_mov_b32_e32 v67, v0
	v_mov_b32_e32 v68, v0
	v_mov_b32_e32 v69, v0
	v_mov_b32_e32 v70, v0
	v_mov_b32_e32 v71, v0
	v_mov_b32_e32 v80, v0
	v_mov_b32_e32 v81, v0
	v_mov_b32_e32 v82, v0
	v_mov_b32_e32 v83, v0
	v_mov_b32_e32 v84, v0
	v_mov_b32_e32 v85, v0
	v_mov_b32_e32 v86, v0
	v_mov_b32_e32 v87, v0
	v_mov_b32_e32 v96, v0
	v_mov_b32_e32 v97, v0
	v_mov_b32_e32 v98, v0
	v_mov_b32_e32 v99, v0
	v_mov_b32_e32 v100, v0
	v_mov_b32_e32 v101, v0
	v_mov_b32_e32 v102, v0
	v_mov_b32_e32 v103, v0
	v_mov_b32_e32 v112, v0
	v_mov_b32_e32 v113, v0
	v_mov_b32_e32 v114, v0
	v_mov_b32_e32 v115, v0
	v_mov_b32_e32 v116, v0
	v_mov_b32_e32 v117, v0
	v_mov_b32_e32 v118, v0
	v_mov_b32_e32 v119, v0
	v_mov_b32_e32 v72, v0
	v_mov_b32_e32 v73, v0
	v_mov_b32_e32 v74, v0
	v_mov_b32_e32 v75, v0
	v_mov_b32_e32 v76, v0
	v_mov_b32_e32 v77, v0
	v_mov_b32_e32 v78, v0
	v_mov_b32_e32 v79, v0
	v_mov_b32_e32 v88, v0
	v_mov_b32_e32 v89, v0
	v_mov_b32_e32 v90, v0
	v_mov_b32_e32 v91, v0
	v_mov_b32_e32 v92, v0
	v_mov_b32_e32 v93, v0
	v_mov_b32_e32 v94, v0
	v_mov_b32_e32 v95, v0
	v_mov_b32_e32 v104, v0
	v_mov_b32_e32 v105, v0
	v_mov_b32_e32 v106, v0
	v_mov_b32_e32 v107, v0
	v_mov_b32_e32 v108, v0
	v_mov_b32_e32 v109, v0
	v_mov_b32_e32 v110, v0
	v_mov_b32_e32 v111, v0
	v_mov_b32_e32 v120, v0
	v_mov_b32_e32 v121, v0
	v_mov_b32_e32 v122, v0
	v_mov_b32_e32 v123, v0
	v_mov_b32_e32 v124, v0
	v_mov_b32_e32 v125, v0
	v_mov_b32_e32 v126, v0
	v_mov_b32_e32 v127, v0
	s_add_u32 s8, s6, 0xfffe0080
	s_addc_u32 s9, s7, -1
	s_add_i32 s70, 0, 0x10000
	s_cmp_eq_u32 s69, 12
	s_cselect_b32 s11, s27, s9
	s_cselect_b32 s10, s26, s8
	s_cselect_b32 s9, s29, s31
	s_cselect_b32 s8, s28, s25
	s_add_i32 s72, 0, 0x14000
.LBB0_990:
	v_add_u32_e32 v148, s70, v134
	v_add_u32_e32 v164, s72, v134
	ds_read_b128 v[136:139], v148
	ds_read_b128 v[140:143], v148 offset:1024
	ds_read_b128 v[144:147], v148 offset:2048
	ds_read_b128 v[148:151], v148 offset:3072
	ds_read_b128 v[152:155], v164
	ds_read_b128 v[156:159], v164 offset:1024
	ds_read_b128 v[160:163], v164 offset:2048
	ds_read_b128 v[164:167], v164 offset:3072
	v_lshl_add_u64 v[174:175], s[6:7], 0, v[172:173]
	s_add_i32 m0, s44, 0xc000
	ds_read_b128 v[168:171], v135
	ds_read_b128 v[188:191], v135 offset:1024
	ds_read_b128 v[204:207], v135 offset:2048
	ds_read_b128 v[208:211], v135 offset:3072
	ds_read_b128 v[212:215], v135 offset:4096
	ds_read_b128 v[216:219], v135 offset:5120
	ds_read_b128 v[220:223], v135 offset:6144
	ds_read_b128 v[224:227], v135 offset:7168
	global_load_lds_dwordx4 v[174:175], off
	v_lshl_add_u64 v[174:175], s[6:7], 0, v[132:133]
	s_add_i32 m0, s44, 0xe000
	s_nop 0
	global_load_lds_dwordx4 v[174:175], off
	s_waitcnt vmcnt(8)
	s_waitcnt lgkmcnt(0)
	s_barrier
	s_setprio 1
	s_waitcnt lgkmcnt(0)
	v_mfma_f32_16x16x32_bf16 v[124:127], v[136:139], v[168:171], v[124:127]
	v_mfma_f32_16x16x32_bf16 v[120:123], v[144:147], v[168:171], v[120:123]
	v_mfma_f32_16x16x32_bf16 v[108:111], v[136:139], v[204:207], v[108:111]
	v_mfma_f32_16x16x32_bf16 v[104:107], v[144:147], v[204:207], v[104:107]
	v_mfma_f32_16x16x32_bf16 v[92:95], v[136:139], v[212:215], v[92:95]
	v_mfma_f32_16x16x32_bf16 v[88:91], v[144:147], v[212:215], v[88:91]
	v_mfma_f32_16x16x32_bf16 v[76:79], v[136:139], v[220:223], v[76:79]
	v_mfma_f32_16x16x32_bf16 v[72:75], v[144:147], v[220:223], v[72:75]
	v_mfma_f32_16x16x32_bf16 v[124:127], v[140:143], v[188:191], v[124:127]
	v_mfma_f32_16x16x32_bf16 v[120:123], v[148:151], v[188:191], v[120:123]
	v_mfma_f32_16x16x32_bf16 v[108:111], v[140:143], v[208:211], v[108:111]
	v_mfma_f32_16x16x32_bf16 v[104:107], v[148:151], v[208:211], v[104:107]
	v_mfma_f32_16x16x32_bf16 v[92:95], v[140:143], v[216:219], v[92:95]
	v_mfma_f32_16x16x32_bf16 v[88:91], v[148:151], v[216:219], v[88:91]
	v_mfma_f32_16x16x32_bf16 v[76:79], v[140:143], v[224:227], v[76:79]
	v_mfma_f32_16x16x32_bf16 v[72:75], v[148:151], v[224:227], v[72:75]
	s_setprio 0
	s_setprio 1
	v_mfma_f32_16x16x32_bf16 v[116:119], v[152:155], v[168:171], v[116:119]
	v_mfma_f32_16x16x32_bf16 v[112:115], v[160:163], v[168:171], v[112:115]
	v_mfma_f32_16x16x32_bf16 v[100:103], v[152:155], v[204:207], v[100:103]
	v_mfma_f32_16x16x32_bf16 v[96:99], v[160:163], v[204:207], v[96:99]
	v_mfma_f32_16x16x32_bf16 v[84:87], v[152:155], v[212:215], v[84:87]
	v_mfma_f32_16x16x32_bf16 v[80:83], v[160:163], v[212:215], v[80:83]
	v_mfma_f32_16x16x32_bf16 v[68:71], v[152:155], v[220:223], v[68:71]
	v_mfma_f32_16x16x32_bf16 v[64:67], v[160:163], v[220:223], v[64:67]
	v_mfma_f32_16x16x32_bf16 v[116:119], v[156:159], v[188:191], v[116:119]
	v_mfma_f32_16x16x32_bf16 v[112:115], v[164:167], v[188:191], v[112:115]
	v_mfma_f32_16x16x32_bf16 v[100:103], v[156:159], v[208:211], v[100:103]
	v_mfma_f32_16x16x32_bf16 v[96:99], v[164:167], v[208:211], v[96:99]
	v_mfma_f32_16x16x32_bf16 v[84:87], v[156:159], v[216:219], v[84:87]
	v_mfma_f32_16x16x32_bf16 v[80:83], v[164:167], v[216:219], v[80:83]
	v_mfma_f32_16x16x32_bf16 v[68:71], v[156:159], v[224:227], v[68:71]
	v_mfma_f32_16x16x32_bf16 v[64:67], v[164:167], v[224:227], v[64:67]
	s_setprio 0
	s_barrier
	s_add_i32 s70, s70, s39
	v_lshl_add_u64 v[174:175], s[8:9], 0, v[128:129]
	s_mov_b32 m0, s70
	ds_read_b128 v[168:171], v135 offset:16384
	ds_read_b128 v[188:191], v135 offset:17408
	ds_read_b128 v[204:207], v135 offset:18432
	ds_read_b128 v[208:211], v135 offset:19456
	ds_read_b128 v[212:215], v135 offset:20480
	ds_read_b128 v[216:219], v135 offset:21504
	ds_read_b128 v[220:223], v135 offset:22528
	ds_read_b128 v[224:227], v135 offset:23552
	global_load_lds_dwordx4 v[174:175], off
	s_add_i32 m0, s70, 0x2000
	s_add_u32 s70, s8, 0x40000
	v_lshl_add_u64 v[176:177], s[8:9], 0, v[130:131]
	s_addc_u32 s71, s9, 0
	s_add_i32 s72, s72, s39
	global_load_lds_dwordx4 v[176:177], off
	v_lshl_add_u64 v[180:181], s[70:71], 0, v[128:129]
	s_mov_b32 m0, s72
	v_lshl_add_u64 v[182:183], s[10:11], 0, v[132:133]
	global_load_lds_dwordx4 v[180:181], off
	v_lshl_add_u64 v[180:181], s[70:71], 0, v[130:131]
	s_add_i32 m0, s72, 0x2000
	s_nop 0
	global_load_lds_dwordx4 v[180:181], off
	v_lshl_add_u64 v[180:181], s[10:11], 0, v[172:173]
	s_mov_b32 m0, s44
	s_nop 0
	global_load_lds_dwordx4 v[180:181], off
	s_mov_b32 m0, s45
	s_nop 0
	global_load_lds_dwordx4 v[182:183], off
	s_waitcnt vmcnt(8)
	s_waitcnt lgkmcnt(0)
	s_barrier
	s_setprio 1
	s_waitcnt lgkmcnt(0)
	v_mfma_f32_16x16x32_bf16 v[60:63], v[136:139], v[168:171], v[60:63]
	v_mfma_f32_16x16x32_bf16 v[56:59], v[144:147], v[168:171], v[56:59]
	v_mfma_f32_16x16x32_bf16 v[44:47], v[136:139], v[204:207], v[44:47]
	v_mfma_f32_16x16x32_bf16 v[40:43], v[144:147], v[204:207], v[40:43]
	v_mfma_f32_16x16x32_bf16 v[28:31], v[136:139], v[212:215], v[28:31]
	v_mfma_f32_16x16x32_bf16 v[24:27], v[144:147], v[212:215], v[24:27]
	v_mfma_f32_16x16x32_bf16 v[4:7], v[136:139], v[220:223], v[4:7]
	v_mfma_f32_16x16x32_bf16 v[12:15], v[144:147], v[220:223], v[12:15]
	v_mfma_f32_16x16x32_bf16 v[60:63], v[140:143], v[188:191], v[60:63]
	v_mfma_f32_16x16x32_bf16 v[56:59], v[148:151], v[188:191], v[56:59]
	v_mfma_f32_16x16x32_bf16 v[44:47], v[140:143], v[208:211], v[44:47]
	v_mfma_f32_16x16x32_bf16 v[40:43], v[148:151], v[208:211], v[40:43]
	v_mfma_f32_16x16x32_bf16 v[28:31], v[140:143], v[216:219], v[28:31]
	v_mfma_f32_16x16x32_bf16 v[24:27], v[148:151], v[216:219], v[24:27]
	v_mfma_f32_16x16x32_bf16 v[4:7], v[140:143], v[224:227], v[4:7]
	v_mfma_f32_16x16x32_bf16 v[12:15], v[148:151], v[224:227], v[12:15]
	s_setprio 0
	s_setprio 1
	v_mfma_f32_16x16x32_bf16 v[52:55], v[152:155], v[168:171], v[52:55]
	v_mfma_f32_16x16x32_bf16 v[48:51], v[160:163], v[168:171], v[48:51]
	v_mfma_f32_16x16x32_bf16 v[36:39], v[152:155], v[204:207], v[36:39]
	v_mfma_f32_16x16x32_bf16 v[32:35], v[160:163], v[204:207], v[32:35]
	v_mfma_f32_16x16x32_bf16 v[20:23], v[152:155], v[212:215], v[20:23]
	v_mfma_f32_16x16x32_bf16 v[16:19], v[160:163], v[212:215], v[16:19]
	v_mfma_f32_16x16x32_bf16 v[8:11], v[152:155], v[220:223], v[8:11]
	v_mfma_f32_16x16x32_bf16 v[0:3], v[160:163], v[220:223], v[0:3]
	v_mfma_f32_16x16x32_bf16 v[52:55], v[156:159], v[188:191], v[52:55]
	v_mfma_f32_16x16x32_bf16 v[48:51], v[164:167], v[188:191], v[48:51]
	v_mfma_f32_16x16x32_bf16 v[36:39], v[156:159], v[208:211], v[36:39]
	v_mfma_f32_16x16x32_bf16 v[32:35], v[164:167], v[208:211], v[32:35]
	v_mfma_f32_16x16x32_bf16 v[20:23], v[156:159], v[216:219], v[20:23]
	v_mfma_f32_16x16x32_bf16 v[16:19], v[164:167], v[216:219], v[16:19]
	v_mfma_f32_16x16x32_bf16 v[8:11], v[156:159], v[224:227], v[8:11]
	v_mfma_f32_16x16x32_bf16 v[0:3], v[164:167], v[224:227], v[0:3]
	s_setprio 0
	s_barrier
	s_add_i32 s70, 0, 0x18000
	s_add_i32 s71, 0, 0x1c000
	v_add_u32_e32 v148, s70, v134
	v_add_u32_e32 v164, s71, v134
	ds_read_b128 v[136:139], v148
	ds_read_b128 v[140:143], v148 offset:1024
	ds_read_b128 v[144:147], v148 offset:2048
	ds_read_b128 v[148:151], v148 offset:3072
	ds_read_b128 v[152:155], v164
	ds_read_b128 v[156:159], v164 offset:1024
	ds_read_b128 v[160:163], v164 offset:2048
	ds_read_b128 v[164:167], v164 offset:3072
	s_add_u32 s10, s10, 0x20000
	s_addc_u32 s11, s11, 0
	s_mov_b32 m0, s54
	v_lshl_add_u64 v[228:229], s[10:11], 0, v[172:173]
	ds_read_b128 v[168:171], v135 offset:32768
	ds_read_b128 v[188:191], v135 offset:33792
	ds_read_b128 v[204:207], v135 offset:34816
	ds_read_b128 v[208:211], v135 offset:35840
	ds_read_b128 v[212:215], v135 offset:36864
	ds_read_b128 v[216:219], v135 offset:37888
	ds_read_b128 v[220:223], v135 offset:38912
	ds_read_b128 v[224:227], v135 offset:39936
	global_load_lds_dwordx4 v[228:229], off
	v_lshl_add_u64 v[228:229], s[10:11], 0, v[132:133]
	s_mov_b32 m0, s55
	s_nop 0
	global_load_lds_dwordx4 v[228:229], off
	s_waitcnt vmcnt(8)
	s_waitcnt lgkmcnt(0)
	s_barrier
	s_setprio 1
	s_waitcnt lgkmcnt(0)
	v_mfma_f32_16x16x32_bf16 v[124:127], v[136:139], v[168:171], v[124:127]
	v_mfma_f32_16x16x32_bf16 v[120:123], v[144:147], v[168:171], v[120:123]
	v_mfma_f32_16x16x32_bf16 v[108:111], v[136:139], v[204:207], v[108:111]
	v_mfma_f32_16x16x32_bf16 v[104:107], v[144:147], v[204:207], v[104:107]
	v_mfma_f32_16x16x32_bf16 v[92:95], v[136:139], v[212:215], v[92:95]
	v_mfma_f32_16x16x32_bf16 v[88:91], v[144:147], v[212:215], v[88:91]
	v_mfma_f32_16x16x32_bf16 v[76:79], v[136:139], v[220:223], v[76:79]
	v_mfma_f32_16x16x32_bf16 v[72:75], v[144:147], v[220:223], v[72:75]
	v_mfma_f32_16x16x32_bf16 v[124:127], v[140:143], v[188:191], v[124:127]
	v_mfma_f32_16x16x32_bf16 v[120:123], v[148:151], v[188:191], v[120:123]
	v_mfma_f32_16x16x32_bf16 v[108:111], v[140:143], v[208:211], v[108:111]
	v_mfma_f32_16x16x32_bf16 v[104:107], v[148:151], v[208:211], v[104:107]
	v_mfma_f32_16x16x32_bf16 v[92:95], v[140:143], v[216:219], v[92:95]
	v_mfma_f32_16x16x32_bf16 v[88:91], v[148:151], v[216:219], v[88:91]
	v_mfma_f32_16x16x32_bf16 v[76:79], v[140:143], v[224:227], v[76:79]
	v_mfma_f32_16x16x32_bf16 v[72:75], v[148:151], v[224:227], v[72:75]
	s_setprio 0
	s_setprio 1
	v_mfma_f32_16x16x32_bf16 v[116:119], v[152:155], v[168:171], v[116:119]
	v_mfma_f32_16x16x32_bf16 v[112:115], v[160:163], v[168:171], v[112:115]
	v_mfma_f32_16x16x32_bf16 v[100:103], v[152:155], v[204:207], v[100:103]
	v_mfma_f32_16x16x32_bf16 v[96:99], v[160:163], v[204:207], v[96:99]
	v_mfma_f32_16x16x32_bf16 v[84:87], v[152:155], v[212:215], v[84:87]
	v_mfma_f32_16x16x32_bf16 v[80:83], v[160:163], v[212:215], v[80:83]
	v_mfma_f32_16x16x32_bf16 v[68:71], v[152:155], v[220:223], v[68:71]
	v_mfma_f32_16x16x32_bf16 v[64:67], v[160:163], v[220:223], v[64:67]
	v_mfma_f32_16x16x32_bf16 v[116:119], v[156:159], v[188:191], v[116:119]
	v_mfma_f32_16x16x32_bf16 v[112:115], v[164:167], v[188:191], v[112:115]
	v_mfma_f32_16x16x32_bf16 v[100:103], v[156:159], v[208:211], v[100:103]
	v_mfma_f32_16x16x32_bf16 v[96:99], v[164:167], v[208:211], v[96:99]
	v_mfma_f32_16x16x32_bf16 v[84:87], v[156:159], v[216:219], v[84:87]
	v_mfma_f32_16x16x32_bf16 v[80:83], v[164:167], v[216:219], v[80:83]
	v_mfma_f32_16x16x32_bf16 v[68:71], v[156:159], v[224:227], v[68:71]
	v_mfma_f32_16x16x32_bf16 v[64:67], v[164:167], v[224:227], v[64:67]
	s_setprio 0
	s_barrier
	s_add_i32 s10, s70, s39
	v_lshl_add_u64 v[174:175], v[174:175], 0, s[94:95]
	s_mov_b32 m0, s10
	ds_read_b128 v[168:171], v135 offset:49152
	ds_read_b128 v[188:191], v135 offset:50176
	ds_read_b128 v[204:207], v135 offset:51200
	ds_read_b128 v[208:211], v135 offset:52224
	ds_read_b128 v[212:215], v135 offset:53248
	ds_read_b128 v[216:219], v135 offset:54272
	ds_read_b128 v[220:223], v135 offset:55296
	ds_read_b128 v[224:227], v135 offset:56320
	global_load_lds_dwordx4 v[174:175], off
	s_add_i32 m0, s10, 0x2000
	s_add_u32 s8, s8, 0x40080
	v_lshl_add_u64 v[174:175], v[176:177], 0, s[94:95]
	s_addc_u32 s9, s9, 0
	s_add_i32 s10, s71, s39
	global_load_lds_dwordx4 v[174:175], off
	v_lshl_add_u64 v[174:175], s[8:9], 0, v[128:129]
	s_mov_b32 m0, s10
	s_nop 0
	global_load_lds_dwordx4 v[174:175], off
	v_lshl_add_u64 v[174:175], s[8:9], 0, v[130:131]
	s_add_i32 m0, s10, 0x2000
	s_nop 0
	global_load_lds_dwordx4 v[174:175], off
	v_lshl_add_u64 v[174:175], v[180:181], 0, s[94:95]
	s_mov_b32 m0, s64
	s_nop 0
	global_load_lds_dwordx4 v[174:175], off
	v_lshl_add_u64 v[174:175], v[182:183], 0, s[94:95]
	s_mov_b32 m0, s65
	s_nop 0
	global_load_lds_dwordx4 v[174:175], off
	s_waitcnt vmcnt(8)
	s_waitcnt lgkmcnt(0)
	s_barrier
	s_setprio 1
	s_waitcnt lgkmcnt(0)
	v_mfma_f32_16x16x32_bf16 v[60:63], v[136:139], v[168:171], v[60:63]
	v_mfma_f32_16x16x32_bf16 v[56:59], v[144:147], v[168:171], v[56:59]
	v_mfma_f32_16x16x32_bf16 v[44:47], v[136:139], v[204:207], v[44:47]
	v_mfma_f32_16x16x32_bf16 v[40:43], v[144:147], v[204:207], v[40:43]
	v_mfma_f32_16x16x32_bf16 v[28:31], v[136:139], v[212:215], v[28:31]
	v_mfma_f32_16x16x32_bf16 v[24:27], v[144:147], v[212:215], v[24:27]
	v_mfma_f32_16x16x32_bf16 v[4:7], v[136:139], v[220:223], v[4:7]
	v_mfma_f32_16x16x32_bf16 v[12:15], v[144:147], v[220:223], v[12:15]
	v_mfma_f32_16x16x32_bf16 v[60:63], v[140:143], v[188:191], v[60:63]
	v_mfma_f32_16x16x32_bf16 v[56:59], v[148:151], v[188:191], v[56:59]
	v_mfma_f32_16x16x32_bf16 v[44:47], v[140:143], v[208:211], v[44:47]
	v_mfma_f32_16x16x32_bf16 v[40:43], v[148:151], v[208:211], v[40:43]
	v_mfma_f32_16x16x32_bf16 v[28:31], v[140:143], v[216:219], v[28:31]
	v_mfma_f32_16x16x32_bf16 v[24:27], v[148:151], v[216:219], v[24:27]
	v_mfma_f32_16x16x32_bf16 v[4:7], v[140:143], v[224:227], v[4:7]
	v_mfma_f32_16x16x32_bf16 v[12:15], v[148:151], v[224:227], v[12:15]
	s_setprio 0
	s_setprio 1
	v_mfma_f32_16x16x32_bf16 v[52:55], v[152:155], v[168:171], v[52:55]
	v_mfma_f32_16x16x32_bf16 v[48:51], v[160:163], v[168:171], v[48:51]
	v_mfma_f32_16x16x32_bf16 v[36:39], v[152:155], v[204:207], v[36:39]
	v_mfma_f32_16x16x32_bf16 v[32:35], v[160:163], v[204:207], v[32:35]
	v_mfma_f32_16x16x32_bf16 v[20:23], v[152:155], v[212:215], v[20:23]
	v_mfma_f32_16x16x32_bf16 v[16:19], v[160:163], v[212:215], v[16:19]
	v_mfma_f32_16x16x32_bf16 v[8:11], v[152:155], v[220:223], v[8:11]
	v_mfma_f32_16x16x32_bf16 v[0:3], v[160:163], v[220:223], v[0:3]
	v_mfma_f32_16x16x32_bf16 v[52:55], v[156:159], v[188:191], v[52:55]
	v_mfma_f32_16x16x32_bf16 v[48:51], v[164:167], v[188:191], v[48:51]
	v_mfma_f32_16x16x32_bf16 v[36:39], v[156:159], v[208:211], v[36:39]
	v_mfma_f32_16x16x32_bf16 v[32:35], v[164:167], v[208:211], v[32:35]
	v_mfma_f32_16x16x32_bf16 v[20:23], v[156:159], v[216:219], v[20:23]
	v_mfma_f32_16x16x32_bf16 v[16:19], v[164:167], v[216:219], v[16:19]
	v_mfma_f32_16x16x32_bf16 v[8:11], v[156:159], v[224:227], v[8:11]
	v_mfma_f32_16x16x32_bf16 v[0:3], v[164:167], v[224:227], v[0:3]
	s_setprio 0
	s_add_i32 s69, s69, 2
	s_add_u32 s6, s6, 0x100
	s_addc_u32 s7, s7, 0
	s_add_u32 s25, s25, 0x100
	s_addc_u32 s31, s31, 0
	s_cmp_gt_u32 s69, 13
	s_cbranch_scc1 .Lkrot5_exit
	s_add_u32 s8, s6, 0xfffe0080
	s_addc_u32 s9, s7, -1
	s_add_i32 s70, 0, 0x10000
	s_cmp_eq_u32 s69, 12
	s_cselect_b32 s11, s27, s9
	s_cselect_b32 s10, s26, s8
	s_cselect_b32 s9, s29, s31
	s_cselect_b32 s8, s28, s25
	s_add_i32 s72, 0, 0x14000
	s_barrier
	s_branch .LBB0_990
.Lkrot5_exit:
	s_barrier
	s_and_b64 vcc, exec, s[22:23]
	s_cbranch_vccz .LBB0_993
	s_barrier

.LBB0_1056:
	s_add_i32 s24, s65, -2
	s_add_u32 s6, s22, 0xb0080
	s_addc_u32 s7, s23, 0
	v_add_u32_e32 v1, s44, v1
	v_add_u32_e32 v134, s54, v0
	s_add_u32 s25, s20, 0x100
	v_mov_b32_e32 v0, 0
	v_mov_b32_e32 v131, v173
	v_mov_b32_e32 v129, v173
	v_mov_b32_e32 v133, v173
	s_addc_u32 s68, s21, 0
	s_mov_b32 s20, 0
	v_add_u32_e32 v135, 0, v1
	v_mov_b32_e32 v1, v0
	v_mov_b32_e32 v2, v0
	v_mov_b32_e32 v3, v0
	v_mov_b32_e32 v4, v0
	v_mov_b32_e32 v5, v0
	v_mov_b32_e32 v6, v0
	v_mov_b32_e32 v7, v0
	v_mov_b32_e32 v8, v0
	v_mov_b32_e32 v9, v0
	v_mov_b32_e32 v10, v0
	v_mov_b32_e32 v11, v0
	v_mov_b32_e32 v16, v0
	v_mov_b32_e32 v17, v0
	v_mov_b32_e32 v18, v0
	v_mov_b32_e32 v19, v0
	v_mov_b32_e32 v24, v0
	v_mov_b32_e32 v25, v0
	v_mov_b32_e32 v26, v0
	v_mov_b32_e32 v27, v0
	v_mov_b32_e32 v32, v0
	v_mov_b32_e32 v33, v0
	v_mov_b32_e32 v34, v0
	v_mov_b32_e32 v35, v0
	v_mov_b32_e32 v40, v0
	v_mov_b32_e32 v41, v0
	v_mov_b32_e32 v42, v0
	v_mov_b32_e32 v43, v0
	v_mov_b32_e32 v48, v0
	v_mov_b32_e32 v49, v0
	v_mov_b32_e32 v50, v0
	v_mov_b32_e32 v51, v0
	v_mov_b32_e32 v12, v0
	v_mov_b32_e32 v13, v0
	v_mov_b32_e32 v14, v0
	v_mov_b32_e32 v15, v0
	v_mov_b32_e32 v20, v0
	v_mov_b32_e32 v21, v0
	v_mov_b32_e32 v22, v0
	v_mov_b32_e32 v23, v0
	v_mov_b32_e32 v28, v0
	v_mov_b32_e32 v29, v0
	v_mov_b32_e32 v30, v0
	v_mov_b32_e32 v31, v0
	v_mov_b32_e32 v36, v0
	v_mov_b32_e32 v37, v0
	v_mov_b32_e32 v38, v0
	v_mov_b32_e32 v39, v0
	v_mov_b32_e32 v44, v0
	v_mov_b32_e32 v45, v0
	v_mov_b32_e32 v46, v0
	v_mov_b32_e32 v47, v0
	v_mov_b32_e32 v52, v0
	v_mov_b32_e32 v53, v0
	v_mov_b32_e32 v54, v0
	v_mov_b32_e32 v55, v0
	v_mov_b32_e32 v56, v0
	v_mov_b32_e32 v57, v0
	v_mov_b32_e32 v58, v0
	v_mov_b32_e32 v59, v0
	v_mov_b32_e32 v60, v0
	v_mov_b32_e32 v61, v0
	v_mov_b32_e32 v62, v0
	v_mov_b32_e32 v63, v0
	v_mov_b32_e32 v64, v0
	v_mov_b32_e32 v65, v0
	v_mov_b32_e32 v66, v0
	v_mov_b32_e32 v67, v0
	v_mov_b32_e32 v68, v0
	v_mov_b32_e32 v69, v0
	v_mov_b32_e32 v70, v0
	v_mov_b32_e32 v71, v0
	v_mov_b32_e32 v72, v0
	v_mov_b32_e32 v73, v0
	v_mov_b32_e32 v74, v0
	v_mov_b32_e32 v75, v0
	v_mov_b32_e32 v80, v0
	v_mov_b32_e32 v81, v0
	v_mov_b32_e32 v82, v0
	v_mov_b32_e32 v83, v0
	v_mov_b32_e32 v88, v0
	v_mov_b32_e32 v89, v0
	v_mov_b32_e32 v90, v0
	v_mov_b32_e32 v91, v0
	v_mov_b32_e32 v96, v0
	v_mov_b32_e32 v97, v0
	v_mov_b32_e32 v98, v0
	v_mov_b32_e32 v99, v0
	v_mov_b32_e32 v104, v0
	v_mov_b32_e32 v105, v0
	v_mov_b32_e32 v106, v0
	v_mov_b32_e32 v107, v0
	v_mov_b32_e32 v112, v0
	v_mov_b32_e32 v113, v0
	v_mov_b32_e32 v114, v0
	v_mov_b32_e32 v115, v0
	v_mov_b32_e32 v76, v0
	v_mov_b32_e32 v77, v0
	v_mov_b32_e32 v78, v0
	v_mov_b32_e32 v79, v0
	v_mov_b32_e32 v84, v0
	v_mov_b32_e32 v85, v0
	v_mov_b32_e32 v86, v0
	v_mov_b32_e32 v87, v0
	v_mov_b32_e32 v92, v0
	v_mov_b32_e32 v93, v0
	v_mov_b32_e32 v94, v0
	v_mov_b32_e32 v95, v0
	v_mov_b32_e32 v100, v0
	v_mov_b32_e32 v101, v0
	v_mov_b32_e32 v102, v0
	v_mov_b32_e32 v103, v0
	v_mov_b32_e32 v108, v0
	v_mov_b32_e32 v109, v0
	v_mov_b32_e32 v110, v0
	v_mov_b32_e32 v111, v0
	v_mov_b32_e32 v116, v0
	v_mov_b32_e32 v117, v0
	v_mov_b32_e32 v118, v0
	v_mov_b32_e32 v119, v0
	v_mov_b32_e32 v120, v0
	v_mov_b32_e32 v121, v0
	v_mov_b32_e32 v122, v0
	v_mov_b32_e32 v123, v0
	v_mov_b32_e32 v124, v0
	v_mov_b32_e32 v125, v0
	v_mov_b32_e32 v126, v0
	v_mov_b32_e32 v127, v0
	s_add_i32 s69, s20, 2
	s_add_u32 s21, s6, 0xfff50080
	s_addc_u32 s22, s7, -1
	s_add_i32 s70, 0, 0x10000
	s_cmp_eq_u32 s24, s20
	s_cselect_b32 s23, s9, s22
	s_cselect_b32 s22, s8, s21
	s_cselect_b32 s21, s19, s68
	s_cselect_b32 s20, s18, s25
	s_add_i32 s72, 0, 0x14000
.LBB0_1057:
	v_add_u32_e32 v148, s70, v134
	v_add_u32_e32 v164, s72, v134
	ds_read_b128 v[136:139], v148
	ds_read_b128 v[140:143], v148 offset:1024
	ds_read_b128 v[144:147], v148 offset:2048
	ds_read_b128 v[148:151], v148 offset:3072
	ds_read_b128 v[152:155], v164
	ds_read_b128 v[156:159], v164 offset:1024
	ds_read_b128 v[160:163], v164 offset:2048
	ds_read_b128 v[164:167], v164 offset:3072
	v_lshl_add_u64 v[220:221], s[6:7], 0, v[172:173]
	s_add_i32 m0, s35, 0xc000
	ds_read_b128 v[168:171], v135
	ds_read_b128 v[174:177], v135 offset:1024
	ds_read_b128 v[180:183], v135 offset:2048
	ds_read_b128 v[188:191], v135 offset:3072
	ds_read_b128 v[204:207], v135 offset:4096
	ds_read_b128 v[208:211], v135 offset:5120
	ds_read_b128 v[212:215], v135 offset:6144
	ds_read_b128 v[216:219], v135 offset:7168
	global_load_lds_dwordx4 v[220:221], off
	v_lshl_add_u64 v[220:221], s[6:7], 0, v[130:131]
	s_add_i32 m0, s35, 0xe000
	s_nop 0
	global_load_lds_dwordx4 v[220:221], off
	s_waitcnt vmcnt(8)
	s_waitcnt lgkmcnt(0)
	s_barrier
	s_setprio 1
	s_waitcnt lgkmcnt(0)
	v_mfma_f32_16x16x32_bf16 v[124:127], v[136:139], v[168:171], v[124:127]
	v_mfma_f32_16x16x32_bf16 v[120:123], v[144:147], v[168:171], v[120:123]
	v_mfma_f32_16x16x32_bf16 v[116:119], v[136:139], v[180:183], v[116:119]
	v_mfma_f32_16x16x32_bf16 v[108:111], v[144:147], v[180:183], v[108:111]
	v_mfma_f32_16x16x32_bf16 v[100:103], v[136:139], v[204:207], v[100:103]
	v_mfma_f32_16x16x32_bf16 v[92:95], v[144:147], v[204:207], v[92:95]
	v_mfma_f32_16x16x32_bf16 v[84:87], v[136:139], v[212:215], v[84:87]
	v_mfma_f32_16x16x32_bf16 v[76:79], v[144:147], v[212:215], v[76:79]
	v_mfma_f32_16x16x32_bf16 v[124:127], v[140:143], v[174:177], v[124:127]
	v_mfma_f32_16x16x32_bf16 v[120:123], v[148:151], v[174:177], v[120:123]
	v_mfma_f32_16x16x32_bf16 v[116:119], v[140:143], v[188:191], v[116:119]
	v_mfma_f32_16x16x32_bf16 v[108:111], v[148:151], v[188:191], v[108:111]
	v_mfma_f32_16x16x32_bf16 v[100:103], v[140:143], v[208:211], v[100:103]
	v_mfma_f32_16x16x32_bf16 v[92:95], v[148:151], v[208:211], v[92:95]
	v_mfma_f32_16x16x32_bf16 v[84:87], v[140:143], v[216:219], v[84:87]
	v_mfma_f32_16x16x32_bf16 v[76:79], v[148:151], v[216:219], v[76:79]
	s_setprio 0
	s_setprio 1
	v_mfma_f32_16x16x32_bf16 v[112:115], v[152:155], v[168:171], v[112:115]
	v_mfma_f32_16x16x32_bf16 v[104:107], v[160:163], v[168:171], v[104:107]
	v_mfma_f32_16x16x32_bf16 v[96:99], v[152:155], v[180:183], v[96:99]
	v_mfma_f32_16x16x32_bf16 v[88:91], v[160:163], v[180:183], v[88:91]
	v_mfma_f32_16x16x32_bf16 v[80:83], v[152:155], v[204:207], v[80:83]
	v_mfma_f32_16x16x32_bf16 v[72:75], v[160:163], v[204:207], v[72:75]
	v_mfma_f32_16x16x32_bf16 v[68:71], v[152:155], v[212:215], v[68:71]
	v_mfma_f32_16x16x32_bf16 v[64:67], v[160:163], v[212:215], v[64:67]
	v_mfma_f32_16x16x32_bf16 v[112:115], v[156:159], v[174:177], v[112:115]
	v_mfma_f32_16x16x32_bf16 v[104:107], v[164:167], v[174:177], v[104:107]
	v_mfma_f32_16x16x32_bf16 v[96:99], v[156:159], v[188:191], v[96:99]
	v_mfma_f32_16x16x32_bf16 v[88:91], v[164:167], v[188:191], v[88:91]
	v_mfma_f32_16x16x32_bf16 v[80:83], v[156:159], v[208:211], v[80:83]
	v_mfma_f32_16x16x32_bf16 v[72:75], v[164:167], v[208:211], v[72:75]
	v_mfma_f32_16x16x32_bf16 v[68:71], v[156:159], v[216:219], v[68:71]
	v_mfma_f32_16x16x32_bf16 v[64:67], v[164:167], v[216:219], v[64:67]
	s_setprio 0
	s_barrier
	s_add_i32 s70, s70, s34
	v_lshl_add_u64 v[220:221], s[20:21], 0, v[128:129]
	s_mov_b32 m0, s70
	ds_read_b128 v[168:171], v135 offset:16384
	ds_read_b128 v[174:177], v135 offset:17408
	ds_read_b128 v[180:183], v135 offset:18432
	ds_read_b128 v[188:191], v135 offset:19456
	ds_read_b128 v[204:207], v135 offset:20480
	ds_read_b128 v[208:211], v135 offset:21504
	ds_read_b128 v[212:215], v135 offset:22528
	ds_read_b128 v[216:219], v135 offset:23552
	global_load_lds_dwordx4 v[220:221], off
	s_add_i32 m0, s70, 0x2000
	s_add_u32 s70, s20, 0xb0000
	v_lshl_add_u64 v[222:223], s[20:21], 0, v[132:133]
	s_addc_u32 s71, s21, 0
	s_add_i32 s72, s72, s34
	global_load_lds_dwordx4 v[222:223], off
	v_lshl_add_u64 v[224:225], s[70:71], 0, v[128:129]
	s_mov_b32 m0, s72
	v_lshl_add_u64 v[226:227], s[22:23], 0, v[130:131]
	global_load_lds_dwordx4 v[224:225], off
	v_lshl_add_u64 v[224:225], s[70:71], 0, v[132:133]
	s_add_i32 m0, s72, 0x2000
	s_nop 0
	global_load_lds_dwordx4 v[224:225], off
	v_lshl_add_u64 v[224:225], s[22:23], 0, v[172:173]
	s_mov_b32 m0, s35
	s_nop 0
	global_load_lds_dwordx4 v[224:225], off
	s_mov_b32 m0, s36
	s_nop 0
	global_load_lds_dwordx4 v[226:227], off
	s_waitcnt vmcnt(8)
	s_waitcnt lgkmcnt(0)
	s_barrier
	s_setprio 1
	s_waitcnt lgkmcnt(0)
	v_mfma_f32_16x16x32_bf16 v[60:63], v[136:139], v[168:171], v[60:63]
	v_mfma_f32_16x16x32_bf16 v[56:59], v[144:147], v[168:171], v[56:59]
	v_mfma_f32_16x16x32_bf16 v[52:55], v[136:139], v[180:183], v[52:55]
	v_mfma_f32_16x16x32_bf16 v[44:47], v[144:147], v[180:183], v[44:47]
	v_mfma_f32_16x16x32_bf16 v[36:39], v[136:139], v[204:207], v[36:39]
	v_mfma_f32_16x16x32_bf16 v[28:31], v[144:147], v[204:207], v[28:31]
	v_mfma_f32_16x16x32_bf16 v[20:23], v[136:139], v[212:215], v[20:23]
	v_mfma_f32_16x16x32_bf16 v[12:15], v[144:147], v[212:215], v[12:15]
	v_mfma_f32_16x16x32_bf16 v[60:63], v[140:143], v[174:177], v[60:63]
	v_mfma_f32_16x16x32_bf16 v[56:59], v[148:151], v[174:177], v[56:59]
	v_mfma_f32_16x16x32_bf16 v[52:55], v[140:143], v[188:191], v[52:55]
	v_mfma_f32_16x16x32_bf16 v[44:47], v[148:151], v[188:191], v[44:47]
	v_mfma_f32_16x16x32_bf16 v[36:39], v[140:143], v[208:211], v[36:39]
	v_mfma_f32_16x16x32_bf16 v[28:31], v[148:151], v[208:211], v[28:31]
	v_mfma_f32_16x16x32_bf16 v[20:23], v[140:143], v[216:219], v[20:23]
	v_mfma_f32_16x16x32_bf16 v[12:15], v[148:151], v[216:219], v[12:15]
	s_setprio 0
	s_setprio 1
	v_mfma_f32_16x16x32_bf16 v[48:51], v[152:155], v[168:171], v[48:51]
	v_mfma_f32_16x16x32_bf16 v[40:43], v[160:163], v[168:171], v[40:43]
	v_mfma_f32_16x16x32_bf16 v[32:35], v[152:155], v[180:183], v[32:35]
	v_mfma_f32_16x16x32_bf16 v[24:27], v[160:163], v[180:183], v[24:27]
	v_mfma_f32_16x16x32_bf16 v[16:19], v[152:155], v[204:207], v[16:19]
	v_mfma_f32_16x16x32_bf16 v[8:11], v[160:163], v[204:207], v[8:11]
	v_mfma_f32_16x16x32_bf16 v[4:7], v[152:155], v[212:215], v[4:7]
	v_mfma_f32_16x16x32_bf16 v[0:3], v[160:163], v[212:215], v[0:3]
	v_mfma_f32_16x16x32_bf16 v[48:51], v[156:159], v[174:177], v[48:51]
	v_mfma_f32_16x16x32_bf16 v[40:43], v[164:167], v[174:177], v[40:43]
	v_mfma_f32_16x16x32_bf16 v[32:35], v[156:159], v[188:191], v[32:35]
	v_mfma_f32_16x16x32_bf16 v[24:27], v[164:167], v[188:191], v[24:27]
	v_mfma_f32_16x16x32_bf16 v[16:19], v[156:159], v[208:211], v[16:19]
	v_mfma_f32_16x16x32_bf16 v[8:11], v[164:167], v[208:211], v[8:11]
	v_mfma_f32_16x16x32_bf16 v[4:7], v[156:159], v[216:219], v[4:7]
	v_mfma_f32_16x16x32_bf16 v[0:3], v[164:167], v[216:219], v[0:3]
	s_setprio 0
	s_barrier
	s_add_i32 s70, 0, 0x18000
	s_add_i32 s71, 0, 0x1c000
	v_add_u32_e32 v148, s70, v134
	v_add_u32_e32 v164, s71, v134
	ds_read_b128 v[136:139], v148
	ds_read_b128 v[140:143], v148 offset:1024
	ds_read_b128 v[144:147], v148 offset:2048
	ds_read_b128 v[148:151], v148 offset:3072
	ds_read_b128 v[152:155], v164
	ds_read_b128 v[156:159], v164 offset:1024
	ds_read_b128 v[160:163], v164 offset:2048
	ds_read_b128 v[164:167], v164 offset:3072
	s_add_u32 s22, s22, 0xb0000
	s_addc_u32 s23, s23, 0
	s_mov_b32 m0, s37
	v_lshl_add_u64 v[228:229], s[22:23], 0, v[172:173]
	ds_read_b128 v[168:171], v135 offset:32768
	ds_read_b128 v[174:177], v135 offset:33792
	ds_read_b128 v[180:183], v135 offset:34816
	ds_read_b128 v[188:191], v135 offset:35840
	ds_read_b128 v[204:207], v135 offset:36864
	ds_read_b128 v[208:211], v135 offset:37888
	ds_read_b128 v[212:215], v135 offset:38912
	ds_read_b128 v[216:219], v135 offset:39936
	global_load_lds_dwordx4 v[228:229], off
	v_lshl_add_u64 v[228:229], s[22:23], 0, v[130:131]
	s_mov_b32 m0, s38
	s_nop 0
	global_load_lds_dwordx4 v[228:229], off
	s_waitcnt vmcnt(8)
	s_waitcnt lgkmcnt(0)
	s_barrier
	s_setprio 1
	s_waitcnt lgkmcnt(0)
	v_mfma_f32_16x16x32_bf16 v[124:127], v[136:139], v[168:171], v[124:127]
	v_mfma_f32_16x16x32_bf16 v[120:123], v[144:147], v[168:171], v[120:123]
	v_mfma_f32_16x16x32_bf16 v[116:119], v[136:139], v[180:183], v[116:119]
	v_mfma_f32_16x16x32_bf16 v[108:111], v[144:147], v[180:183], v[108:111]
	v_mfma_f32_16x16x32_bf16 v[100:103], v[136:139], v[204:207], v[100:103]
	v_mfma_f32_16x16x32_bf16 v[92:95], v[144:147], v[204:207], v[92:95]
	v_mfma_f32_16x16x32_bf16 v[84:87], v[136:139], v[212:215], v[84:87]
	v_mfma_f32_16x16x32_bf16 v[76:79], v[144:147], v[212:215], v[76:79]
	v_mfma_f32_16x16x32_bf16 v[124:127], v[140:143], v[174:177], v[124:127]
	v_mfma_f32_16x16x32_bf16 v[120:123], v[148:151], v[174:177], v[120:123]
	v_mfma_f32_16x16x32_bf16 v[116:119], v[140:143], v[188:191], v[116:119]
	v_mfma_f32_16x16x32_bf16 v[108:111], v[148:151], v[188:191], v[108:111]
	v_mfma_f32_16x16x32_bf16 v[100:103], v[140:143], v[208:211], v[100:103]
	v_mfma_f32_16x16x32_bf16 v[92:95], v[148:151], v[208:211], v[92:95]
	v_mfma_f32_16x16x32_bf16 v[84:87], v[140:143], v[216:219], v[84:87]
	v_mfma_f32_16x16x32_bf16 v[76:79], v[148:151], v[216:219], v[76:79]
	s_setprio 0
	s_setprio 1
	v_mfma_f32_16x16x32_bf16 v[112:115], v[152:155], v[168:171], v[112:115]
	v_mfma_f32_16x16x32_bf16 v[104:107], v[160:163], v[168:171], v[104:107]
	v_mfma_f32_16x16x32_bf16 v[96:99], v[152:155], v[180:183], v[96:99]
	v_mfma_f32_16x16x32_bf16 v[88:91], v[160:163], v[180:183], v[88:91]
	v_mfma_f32_16x16x32_bf16 v[80:83], v[152:155], v[204:207], v[80:83]
	v_mfma_f32_16x16x32_bf16 v[72:75], v[160:163], v[204:207], v[72:75]
	v_mfma_f32_16x16x32_bf16 v[68:71], v[152:155], v[212:215], v[68:71]
	v_mfma_f32_16x16x32_bf16 v[64:67], v[160:163], v[212:215], v[64:67]
	v_mfma_f32_16x16x32_bf16 v[112:115], v[156:159], v[174:177], v[112:115]
	v_mfma_f32_16x16x32_bf16 v[104:107], v[164:167], v[174:177], v[104:107]
	v_mfma_f32_16x16x32_bf16 v[96:99], v[156:159], v[188:191], v[96:99]
	v_mfma_f32_16x16x32_bf16 v[88:91], v[164:167], v[188:191], v[88:91]
	v_mfma_f32_16x16x32_bf16 v[80:83], v[156:159], v[208:211], v[80:83]
	v_mfma_f32_16x16x32_bf16 v[72:75], v[164:167], v[208:211], v[72:75]
	v_mfma_f32_16x16x32_bf16 v[68:71], v[156:159], v[216:219], v[68:71]
	v_mfma_f32_16x16x32_bf16 v[64:67], v[164:167], v[216:219], v[64:67]
	s_setprio 0
	s_barrier
	s_add_i32 s22, s70, s34
	v_lshl_add_u64 v[220:221], v[220:221], 0, s[94:95]
	s_mov_b32 m0, s22
	ds_read_b128 v[168:171], v135 offset:49152
	ds_read_b128 v[174:177], v135 offset:50176
	ds_read_b128 v[180:183], v135 offset:51200
	ds_read_b128 v[188:191], v135 offset:52224
	ds_read_b128 v[204:207], v135 offset:53248
	ds_read_b128 v[208:211], v135 offset:54272
	ds_read_b128 v[212:215], v135 offset:55296
	ds_read_b128 v[216:219], v135 offset:56320
	global_load_lds_dwordx4 v[220:221], off
	s_add_i32 m0, s22, 0x2000
	s_add_u32 s20, s20, 0xb0080
	v_lshl_add_u64 v[220:221], v[222:223], 0, s[94:95]
	s_addc_u32 s21, s21, 0
	s_add_i32 s22, s71, s34
	global_load_lds_dwordx4 v[220:221], off
	v_lshl_add_u64 v[220:221], s[20:21], 0, v[128:129]
	s_mov_b32 m0, s22
	s_nop 0
	global_load_lds_dwordx4 v[220:221], off
	v_lshl_add_u64 v[220:221], s[20:21], 0, v[132:133]
	s_add_i32 m0, s22, 0x2000
	s_nop 0
	global_load_lds_dwordx4 v[220:221], off
	v_lshl_add_u64 v[220:221], v[224:225], 0, s[94:95]
	s_mov_b32 m0, s55
	s_nop 0
	global_load_lds_dwordx4 v[220:221], off
	v_lshl_add_u64 v[220:221], v[226:227], 0, s[94:95]
	s_mov_b32 m0, s56
	s_nop 0
	global_load_lds_dwordx4 v[220:221], off
	s_waitcnt vmcnt(8)
	s_waitcnt lgkmcnt(0)
	s_barrier
	s_setprio 1
	s_waitcnt lgkmcnt(0)
	v_mfma_f32_16x16x32_bf16 v[60:63], v[136:139], v[168:171], v[60:63]
	v_mfma_f32_16x16x32_bf16 v[56:59], v[144:147], v[168:171], v[56:59]
	v_mfma_f32_16x16x32_bf16 v[52:55], v[136:139], v[180:183], v[52:55]
	v_mfma_f32_16x16x32_bf16 v[44:47], v[144:147], v[180:183], v[44:47]
	v_mfma_f32_16x16x32_bf16 v[36:39], v[136:139], v[204:207], v[36:39]
	v_mfma_f32_16x16x32_bf16 v[28:31], v[144:147], v[204:207], v[28:31]
	v_mfma_f32_16x16x32_bf16 v[20:23], v[136:139], v[212:215], v[20:23]
	v_mfma_f32_16x16x32_bf16 v[12:15], v[144:147], v[212:215], v[12:15]
	v_mfma_f32_16x16x32_bf16 v[60:63], v[140:143], v[174:177], v[60:63]
	v_mfma_f32_16x16x32_bf16 v[56:59], v[148:151], v[174:177], v[56:59]
	v_mfma_f32_16x16x32_bf16 v[52:55], v[140:143], v[188:191], v[52:55]
	v_mfma_f32_16x16x32_bf16 v[44:47], v[148:151], v[188:191], v[44:47]
	v_mfma_f32_16x16x32_bf16 v[36:39], v[140:143], v[208:211], v[36:39]
	v_mfma_f32_16x16x32_bf16 v[28:31], v[148:151], v[208:211], v[28:31]
	v_mfma_f32_16x16x32_bf16 v[20:23], v[140:143], v[216:219], v[20:23]
	v_mfma_f32_16x16x32_bf16 v[12:15], v[148:151], v[216:219], v[12:15]
	s_setprio 0
	s_setprio 1
	v_mfma_f32_16x16x32_bf16 v[48:51], v[152:155], v[168:171], v[48:51]
	v_mfma_f32_16x16x32_bf16 v[40:43], v[160:163], v[168:171], v[40:43]
	v_mfma_f32_16x16x32_bf16 v[32:35], v[152:155], v[180:183], v[32:35]
	v_mfma_f32_16x16x32_bf16 v[24:27], v[160:163], v[180:183], v[24:27]
	v_mfma_f32_16x16x32_bf16 v[16:19], v[152:155], v[204:207], v[16:19]
	v_mfma_f32_16x16x32_bf16 v[8:11], v[160:163], v[204:207], v[8:11]
	v_mfma_f32_16x16x32_bf16 v[4:7], v[152:155], v[212:215], v[4:7]
	v_mfma_f32_16x16x32_bf16 v[0:3], v[160:163], v[212:215], v[0:3]
	v_mfma_f32_16x16x32_bf16 v[48:51], v[156:159], v[174:177], v[48:51]
	v_mfma_f32_16x16x32_bf16 v[40:43], v[164:167], v[174:177], v[40:43]
	v_mfma_f32_16x16x32_bf16 v[32:35], v[156:159], v[188:191], v[32:35]
	v_mfma_f32_16x16x32_bf16 v[24:27], v[164:167], v[188:191], v[24:27]
	v_mfma_f32_16x16x32_bf16 v[16:19], v[156:159], v[208:211], v[16:19]
	v_mfma_f32_16x16x32_bf16 v[8:11], v[164:167], v[208:211], v[8:11]
	v_mfma_f32_16x16x32_bf16 v[4:7], v[156:159], v[216:219], v[4:7]
	v_mfma_f32_16x16x32_bf16 v[0:3], v[164:167], v[216:219], v[0:3]
	s_setprio 0
	s_add_u32 s6, s6, 0x100
	s_addc_u32 s7, s7, 0
	s_add_u32 s25, s25, 0x100
	s_addc_u32 s68, s68, 0
	s_cmp_ge_i32 s69, s65
	s_mov_b32 s20, s69
	s_cbranch_scc1 .Lkrot6_exit
	s_add_i32 s69, s20, 2
	s_add_u32 s21, s6, 0xfff50080
	s_addc_u32 s22, s7, -1
	s_add_i32 s70, 0, 0x10000
	s_cmp_eq_u32 s24, s20
	s_cselect_b32 s23, s9, s22
	s_cselect_b32 s22, s8, s21
	s_cselect_b32 s21, s19, s68
	s_cselect_b32 s20, s18, s25
	s_add_i32 s72, 0, 0x14000
	s_barrier
	s_branch .LBB0_1057
